# v40 with the sc1 write-through bit removed from the 128 residual-epilogue stores (plain write-back stores)
# speedup vs baseline: 1.0004x; 1.0004x over previous
; #define PG8_STAGE(bufoff, gbase) do { _Pragma("unroll") for (int _i = 0; _i < 2; ++_i) \
;         __builtin_amdgcn_global_load_lds((const unsigned*)((const char*)(gbase) + voff[_i]), (LAS unsigned*)(lds + (bufoff) + ldsw + _i * 8192), 16, 0, 0); } while (0)
; #define PG8_LDA(dst, b, h) do { _Pragma("unroll") for (int m = 0; m < 4; ++m) _Pragma("unroll") for (int k = 0; k < 2; ++k) dst[m][k] = *(const LAS bf16x8*)(lds + PG8_SA(b, h) + aoff + m * 2048 + k * 1024); } while (0)
; #define PG8_LDB(dst, b, h) do { _Pragma("unroll") for (int n = 0; n < 2; ++n) _Pragma("unroll") for (int k = 0; k < 2; ++k) dst[n][k] = *(const LAS bf16x8*)(lds + PG8_SB(b, h) + boff + n * 2048 + k * 1024); } while (0)
; #define PG8_WAIT_V(n) asm volatile("s_waitcnt vmcnt(" #n ")" ::: "memory")
; #define PG8_WAIT_L(n) asm volatile("s_waitcnt lgkmcnt(" #n ")" ::: "memory")
; #define PG8_BAR __builtin_amdgcn_s_barrier()
; #define PG8_SCHED __builtin_amdgcn_sched_barrier(0)
;     ...
;         for (int t = 0; t < nt; t += 2) {
;             const bool last = (t == nt - 2);
;             const char* a1 = cA + (size_t)(t + 1) * kstep;
;             const char* a2 = last ? nA : cA + (size_t)(t + 2) * kstep; const char* b2 = last ? nB : cB + (size_t)(t + 2) * kstep;
;             const char* a3 = a2 + kstep; const char* b3 = b2 + kstep;
;             PG8_LDB(B0, 0, 0); PG8_SCHED; PG8_LDA(At, 0, 0); PG8_STAGE(PG8_SA(1, 1), a1 + hstep);
;             PG8_WAIT_L(8); PG8_BAR; PG8_WAIT_L(0); PG8_MMA(0, 0, At, B0); PG8_BAR; PG8_SCHED;
;             PG8_LDB(B1, 0, 1); PG8_STAGE(PG8_SB(0, 0), b2);
;             PG8_BAR; PG8_WAIT_L(0); PG8_MMA(0, 1, At, B1); PG8_BAR;
;             PG8_LDA(At, 0, 1); PG8_STAGE(PG8_SA(0, 0), a2);
;             PG8_BAR; PG8_WAIT_L(0); PG8_MMA(1, 0, At, B0); PG8_BAR; PG8_SCHED;
;             PG8_STAGE(PG8_SB(0, 1), b2 + hstep);
;             PG8_WAIT_V(6); PG8_BAR; PG8_MMA(1, 1, At, B1); PG8_BAR;
;             PG8_LDB(B0, 1, 0); PG8_SCHED; PG8_LDA(At, 1, 0); PG8_STAGE(PG8_SA(0, 1), a2 + hstep);
;             PG8_WAIT_L(8); PG8_BAR; PG8_WAIT_L(0); PG8_MMA(0, 0, At, B0); PG8_BAR; PG8_SCHED;
.LBB0_1245:
	s_add_i32 s67, s46, 2
	s_add_u32 s0, s40, 0x80
	s_addc_u32 s1, s41, 0
	s_add_i32 s68, 0, 0x10000
	v_add_u32_e32 v169, s68, v166
	ds_read_b128 v[130:133], v169
	ds_read_b128 v[158:161], v169 offset:1024
	ds_read_b128 v[162:165], v169 offset:2048
	ds_read_b128 v[170:173], v169 offset:3072
	s_cmp_eq_u32 s30, s46
	s_cselect_b32 s46, s12, s0
	s_cselect_b32 s47, s13, s1
	s_cselect_b32 s49, s15, s59
	s_cselect_b32 s48, s14, s58
	v_lshl_add_u64 v[174:175], s[40:41], 0, v[154:155]
	s_add_i32 m0, s23, 0xc000
	ds_read_b128 v[194:197], v168
	ds_read_b128 v[198:201], v168 offset:1024
	ds_read_b128 v[202:205], v168 offset:2048
	ds_read_b128 v[206:209], v168 offset:3072
	ds_read_b128 v[210:213], v168 offset:4096
	ds_read_b128 v[214:217], v168 offset:5120
	ds_read_b128 v[218:221], v168 offset:6144
	ds_read_b128 v[222:225], v168 offset:7168
	global_load_lds_dwordx4 v[174:175], off
	s_add_i32 m0, s23, 0xe000
	v_lshl_add_u64 v[174:175], s[40:41], 0, v[156:157]
	global_load_lds_dwordx4 v[174:175], off
	s_waitcnt lgkmcnt(8)
	s_barrier
	s_waitcnt lgkmcnt(0)
	s_setprio 1
	v_mfma_f32_16x16x32_bf16 v[126:129], v[130:133], v[194:197], v[126:129]
	v_mfma_f32_16x16x32_bf16 v[98:101], v[162:165], v[194:197], v[98:101]
	v_mfma_f32_16x16x32_bf16 v[122:125], v[130:133], v[202:205], v[122:125]
	v_mfma_f32_16x16x32_bf16 v[94:97], v[162:165], v[202:205], v[94:97]
	v_mfma_f32_16x16x32_bf16 v[118:121], v[130:133], v[210:213], v[118:121]
	v_mfma_f32_16x16x32_bf16 v[90:93], v[162:165], v[210:213], v[90:93]
	v_mfma_f32_16x16x32_bf16 v[114:117], v[130:133], v[218:221], v[114:117]
	v_mfma_f32_16x16x32_bf16 v[82:85], v[162:165], v[218:221], v[82:85]
	v_mfma_f32_16x16x32_bf16 v[126:129], v[158:161], v[198:201], v[126:129]
	v_mfma_f32_16x16x32_bf16 v[98:101], v[170:173], v[198:201], v[98:101]
	v_mfma_f32_16x16x32_bf16 v[122:125], v[158:161], v[206:209], v[122:125]
	v_mfma_f32_16x16x32_bf16 v[94:97], v[170:173], v[206:209], v[94:97]
	v_mfma_f32_16x16x32_bf16 v[118:121], v[158:161], v[214:217], v[118:121]
	v_mfma_f32_16x16x32_bf16 v[90:93], v[170:173], v[214:217], v[90:93]
	v_mfma_f32_16x16x32_bf16 v[114:117], v[158:161], v[222:225], v[114:117]
	v_mfma_f32_16x16x32_bf16 v[82:85], v[170:173], v[222:225], v[82:85]
	s_setprio 0
	s_barrier
	s_add_i32 s69, 0, 0x14000
	s_add_i32 s0, s68, s18
	v_add_u32_e32 v169, s69, v166
	v_lshl_add_u64 v[174:175], s[48:49], 0, v[152:153]
	s_mov_b32 m0, s0
	ds_read_b128 v[226:229], v169
	ds_read_b128 v[230:233], v169 offset:1024
	ds_read_b128 v[234:237], v169 offset:2048
	ds_read_b128 v[238:241], v169 offset:3072
	global_load_lds_dwordx4 v[174:175], off
	s_add_i32 m0, s0, 0x2000
	v_lshl_add_u64 v[192:193], s[48:49], 0, v[150:151]
	global_load_lds_dwordx4 v[192:193], off
	s_barrier
	s_waitcnt lgkmcnt(0)
	s_setprio 1
	v_mfma_f32_16x16x32_bf16 v[74:77], v[226:229], v[194:197], v[74:77]
	v_mfma_f32_16x16x32_bf16 v[46:49], v[234:237], v[194:197], v[46:49]
	v_mfma_f32_16x16x32_bf16 v[66:69], v[226:229], v[202:205], v[66:69]
	v_mfma_f32_16x16x32_bf16 v[38:41], v[234:237], v[202:205], v[38:41]
	v_mfma_f32_16x16x32_bf16 v[58:61], v[226:229], v[210:213], v[58:61]
	v_mfma_f32_16x16x32_bf16 v[30:33], v[234:237], v[210:213], v[30:33]
	v_mfma_f32_16x16x32_bf16 v[50:53], v[226:229], v[218:221], v[50:53]
	v_mfma_f32_16x16x32_bf16 v[22:25], v[234:237], v[218:221], v[22:25]
	v_mfma_f32_16x16x32_bf16 v[74:77], v[230:233], v[198:201], v[74:77]
	v_mfma_f32_16x16x32_bf16 v[46:49], v[238:241], v[198:201], v[46:49]
	v_mfma_f32_16x16x32_bf16 v[66:69], v[230:233], v[206:209], v[66:69]
	v_mfma_f32_16x16x32_bf16 v[38:41], v[238:241], v[206:209], v[38:41]
	v_mfma_f32_16x16x32_bf16 v[58:61], v[230:233], v[214:217], v[58:61]
	v_mfma_f32_16x16x32_bf16 v[30:33], v[238:241], v[214:217], v[30:33]
	v_mfma_f32_16x16x32_bf16 v[50:53], v[230:233], v[222:225], v[50:53]
	v_mfma_f32_16x16x32_bf16 v[22:25], v[238:241], v[222:225], v[22:25]
	s_setprio 0
	s_mov_b32 m0, s23
	v_lshl_add_u64 v[242:243], s[46:47], 0, v[152:153]
	s_barrier
	ds_read_b128 v[194:197], v168 offset:16384
	ds_read_b128 v[198:201], v168 offset:17408
	ds_read_b128 v[202:205], v168 offset:18432
	ds_read_b128 v[206:209], v168 offset:19456
	ds_read_b128 v[210:213], v168 offset:20480
	ds_read_b128 v[214:217], v168 offset:21504
	ds_read_b128 v[218:221], v168 offset:22528
	ds_read_b128 v[222:225], v168 offset:23552
	global_load_lds_dwordx4 v[242:243], off
	s_mov_b32 m0, s36
	v_lshl_add_u64 v[244:245], s[46:47], 0, v[150:151]
	global_load_lds_dwordx4 v[244:245], off
	s_barrier
	s_waitcnt lgkmcnt(0)
	s_setprio 1
	v_mfma_f32_16x16x32_bf16 v[110:113], v[130:133], v[194:197], v[110:113]
	v_mfma_f32_16x16x32_bf16 v[78:81], v[162:165], v[194:197], v[78:81]
	v_mfma_f32_16x16x32_bf16 v[106:109], v[130:133], v[202:205], v[106:109]
	v_mfma_f32_16x16x32_bf16 v[70:73], v[162:165], v[202:205], v[70:73]
	v_mfma_f32_16x16x32_bf16 v[102:105], v[130:133], v[210:213], v[102:105]
	v_mfma_f32_16x16x32_bf16 v[62:65], v[162:165], v[210:213], v[62:65]
	v_mfma_f32_16x16x32_bf16 v[86:89], v[130:133], v[218:221], v[86:89]
	v_mfma_f32_16x16x32_bf16 v[54:57], v[162:165], v[218:221], v[54:57]
	v_mfma_f32_16x16x32_bf16 v[110:113], v[158:161], v[198:201], v[110:113]
	v_mfma_f32_16x16x32_bf16 v[78:81], v[170:173], v[198:201], v[78:81]
	v_mfma_f32_16x16x32_bf16 v[106:109], v[158:161], v[206:209], v[106:109]
	v_mfma_f32_16x16x32_bf16 v[70:73], v[170:173], v[206:209], v[70:73]
	v_mfma_f32_16x16x32_bf16 v[102:105], v[158:161], v[214:217], v[102:105]
	v_mfma_f32_16x16x32_bf16 v[62:65], v[170:173], v[214:217], v[62:65]
	v_mfma_f32_16x16x32_bf16 v[86:89], v[158:161], v[222:225], v[86:89]
	v_mfma_f32_16x16x32_bf16 v[54:57], v[170:173], v[222:225], v[54:57]
	s_setprio 0
	s_barrier
; #define PG8_STAGE(bufoff, gbase) do { _Pragma("unroll") for (int _i = 0; _i < 2; ++_i) \
;         __builtin_amdgcn_global_load_lds((const unsigned*)((const char*)(gbase) + voff[_i]), (LAS unsigned*)(lds + (bufoff) + ldsw + _i * 8192), 16, 0, 0); } while (0)
; #define PG8_LDA(dst, b, h) do { _Pragma("unroll") for (int m = 0; m < 4; ++m) _Pragma("unroll") for (int k = 0; k < 2; ++k) dst[m][k] = *(const LAS bf16x8*)(lds + PG8_SA(b, h) + aoff + m * 2048 + k * 1024); } while (0)
; #define PG8_LDB(dst, b, h) do { _Pragma("unroll") for (int n = 0; n < 2; ++n) _Pragma("unroll") for (int k = 0; k < 2; ++k) dst[n][k] = *(const LAS bf16x8*)(lds + PG8_SB(b, h) + boff + n * 2048 + k * 1024); } while (0)
; #define PG8_WAIT_V(n) asm volatile("s_waitcnt vmcnt(" #n ")" ::: "memory")
; #define PG8_WAIT_L(n) asm volatile("s_waitcnt lgkmcnt(" #n ")" ::: "memory")
; #define PG8_BAR __builtin_amdgcn_s_barrier()
; #define PG8_SCHED __builtin_amdgcn_sched_barrier(0)
;     ...
;             PG8_WAIT_V(6); PG8_BAR; PG8_MMA(1, 1, At, B1); PG8_BAR;
;             PG8_LDB(B0, 1, 0); PG8_SCHED; PG8_LDA(At, 1, 0); PG8_STAGE(PG8_SA(0, 1), a2 + hstep);
;             PG8_WAIT_L(8); PG8_BAR; PG8_WAIT_L(0); PG8_MMA(0, 0, At, B0); PG8_BAR; PG8_SCHED;
;             PG8_LDB(B1, 1, 1); PG8_STAGE(PG8_SB(1, 0), b3);
;             PG8_BAR; PG8_WAIT_L(0); PG8_MMA(0, 1, At, B1); PG8_BAR;
;             PG8_LDA(At, 1, 1); PG8_STAGE(PG8_SA(1, 0), a3);
;             PG8_BAR; PG8_WAIT_L(0); PG8_MMA(1, 0, At, B0); PG8_BAR; PG8_SCHED;
	s_add_u32 s0, s48, s20
	s_addc_u32 s1, s49, 0
	s_add_i32 s48, s69, s18
	v_lshl_add_u64 v[246:247], s[0:1], 0, v[152:153]
	s_mov_b32 m0, s48
	v_lshl_add_u64 v[248:249], s[0:1], 0, v[150:151]
	global_load_lds_dwordx4 v[246:247], off
	s_add_i32 m0, s48, 0x2000
	s_nop 0
	global_load_lds_dwordx4 v[248:249], off
	s_waitcnt vmcnt(6)
	s_barrier
	s_setprio 1
	v_mfma_f32_16x16x32_bf16 v[42:45], v[226:229], v[194:197], v[42:45]
	v_mfma_f32_16x16x32_bf16 v[14:17], v[234:237], v[194:197], v[14:17]
	v_mfma_f32_16x16x32_bf16 v[34:37], v[226:229], v[202:205], v[34:37]
	v_mfma_f32_16x16x32_bf16 v[10:13], v[234:237], v[202:205], v[10:13]
	v_mfma_f32_16x16x32_bf16 v[26:29], v[226:229], v[210:213], v[26:29]
	v_mfma_f32_16x16x32_bf16 v[6:9], v[234:237], v[210:213], v[6:9]
	v_mfma_f32_16x16x32_bf16 v[18:21], v[226:229], v[218:221], v[18:21]
	v_mfma_f32_16x16x32_bf16 v[2:5], v[234:237], v[218:221], v[2:5]
	v_mfma_f32_16x16x32_bf16 v[42:45], v[230:233], v[198:201], v[42:45]
	v_mfma_f32_16x16x32_bf16 v[14:17], v[238:241], v[198:201], v[14:17]
	v_mfma_f32_16x16x32_bf16 v[34:37], v[230:233], v[206:209], v[34:37]
	v_mfma_f32_16x16x32_bf16 v[10:13], v[238:241], v[206:209], v[10:13]
	v_mfma_f32_16x16x32_bf16 v[26:29], v[230:233], v[214:217], v[26:29]
	v_mfma_f32_16x16x32_bf16 v[6:9], v[238:241], v[214:217], v[6:9]
	v_mfma_f32_16x16x32_bf16 v[18:21], v[230:233], v[222:225], v[18:21]
	v_mfma_f32_16x16x32_bf16 v[2:5], v[238:241], v[222:225], v[2:5]
	s_setprio 0
	s_add_i32 s48, 0, 0x18000
	v_add_u32_e32 v169, s48, v166
	s_barrier
	ds_read_b128 v[130:133], v169
	ds_read_b128 v[158:161], v169 offset:1024
	ds_read_b128 v[162:165], v169 offset:2048
	ds_read_b128 v[170:173], v169 offset:3072
	s_add_u32 s0, s46, s20
	s_addc_u32 s1, s47, 0
	s_mov_b32 m0, s60
	v_lshl_add_u64 v[226:227], s[0:1], 0, v[152:153]
	ds_read_b128 v[194:197], v168 offset:32768
	ds_read_b128 v[198:201], v168 offset:33792
	ds_read_b128 v[202:205], v168 offset:34816
	ds_read_b128 v[206:209], v168 offset:35840
	ds_read_b128 v[210:213], v168 offset:36864
	ds_read_b128 v[214:217], v168 offset:37888
	ds_read_b128 v[218:221], v168 offset:38912
	ds_read_b128 v[222:225], v168 offset:39936
	global_load_lds_dwordx4 v[226:227], off
	s_mov_b32 m0, s61
	v_lshl_add_u64 v[226:227], s[0:1], 0, v[150:151]
	global_load_lds_dwordx4 v[226:227], off
	s_waitcnt lgkmcnt(8)
	s_barrier
	s_waitcnt lgkmcnt(0)
	s_setprio 1
	v_mfma_f32_16x16x32_bf16 v[126:129], v[130:133], v[194:197], v[126:129]
	v_mfma_f32_16x16x32_bf16 v[98:101], v[162:165], v[194:197], v[98:101]
	v_mfma_f32_16x16x32_bf16 v[122:125], v[130:133], v[202:205], v[122:125]
	v_mfma_f32_16x16x32_bf16 v[94:97], v[162:165], v[202:205], v[94:97]
	v_mfma_f32_16x16x32_bf16 v[118:121], v[130:133], v[210:213], v[118:121]
	v_mfma_f32_16x16x32_bf16 v[90:93], v[162:165], v[210:213], v[90:93]
	v_mfma_f32_16x16x32_bf16 v[114:117], v[130:133], v[218:221], v[114:117]
	v_mfma_f32_16x16x32_bf16 v[82:85], v[162:165], v[218:221], v[82:85]
	v_mfma_f32_16x16x32_bf16 v[126:129], v[158:161], v[198:201], v[126:129]
	v_mfma_f32_16x16x32_bf16 v[98:101], v[170:173], v[198:201], v[98:101]
	v_mfma_f32_16x16x32_bf16 v[122:125], v[158:161], v[206:209], v[122:125]
	v_mfma_f32_16x16x32_bf16 v[94:97], v[170:173], v[206:209], v[94:97]
	v_mfma_f32_16x16x32_bf16 v[118:121], v[158:161], v[214:217], v[118:121]
	v_mfma_f32_16x16x32_bf16 v[90:93], v[170:173], v[214:217], v[90:93]
	v_mfma_f32_16x16x32_bf16 v[114:117], v[158:161], v[222:225], v[114:117]
	v_mfma_f32_16x16x32_bf16 v[82:85], v[170:173], v[222:225], v[82:85]
	s_setprio 0
	s_barrier
	s_add_i32 s0, 0, 0x1c000
	s_add_i32 s1, s48, s18
	v_add_u32_e32 v169, s0, v166
	v_lshl_add_u64 v[174:175], v[174:175], 0, s[88:89]
	s_mov_b32 m0, s1
	ds_read_b128 v[226:229], v169
	ds_read_b128 v[230:233], v169 offset:1024
	ds_read_b128 v[234:237], v169 offset:2048
	ds_read_b128 v[238:241], v169 offset:3072
	global_load_lds_dwordx4 v[174:175], off
	s_add_i32 m0, s1, 0x2000
	v_lshl_add_u64 v[174:175], v[192:193], 0, s[88:89]
	global_load_lds_dwordx4 v[174:175], off
	s_barrier
	s_waitcnt lgkmcnt(0)
	s_setprio 1
	v_mfma_f32_16x16x32_bf16 v[74:77], v[226:229], v[194:197], v[74:77]
	v_mfma_f32_16x16x32_bf16 v[46:49], v[234:237], v[194:197], v[46:49]
	v_mfma_f32_16x16x32_bf16 v[66:69], v[226:229], v[202:205], v[66:69]
	v_mfma_f32_16x16x32_bf16 v[38:41], v[234:237], v[202:205], v[38:41]
	v_mfma_f32_16x16x32_bf16 v[58:61], v[226:229], v[210:213], v[58:61]
	v_mfma_f32_16x16x32_bf16 v[30:33], v[234:237], v[210:213], v[30:33]
	v_mfma_f32_16x16x32_bf16 v[50:53], v[226:229], v[218:221], v[50:53]
	v_mfma_f32_16x16x32_bf16 v[22:25], v[234:237], v[218:221], v[22:25]
	v_mfma_f32_16x16x32_bf16 v[74:77], v[230:233], v[198:201], v[74:77]
	v_mfma_f32_16x16x32_bf16 v[46:49], v[238:241], v[198:201], v[46:49]
	v_mfma_f32_16x16x32_bf16 v[66:69], v[230:233], v[206:209], v[66:69]
	v_mfma_f32_16x16x32_bf16 v[38:41], v[238:241], v[206:209], v[38:41]
	v_mfma_f32_16x16x32_bf16 v[58:61], v[230:233], v[214:217], v[58:61]
	v_mfma_f32_16x16x32_bf16 v[30:33], v[238:241], v[214:217], v[30:33]
	v_mfma_f32_16x16x32_bf16 v[50:53], v[230:233], v[222:225], v[50:53]
	v_mfma_f32_16x16x32_bf16 v[22:25], v[238:241], v[222:225], v[22:25]
	s_setprio 0
	s_mov_b32 m0, s28
	v_lshl_add_u64 v[174:175], v[242:243], 0, s[88:89]
	s_barrier
	ds_read_b128 v[194:197], v168 offset:49152
	ds_read_b128 v[198:201], v168 offset:50176
	ds_read_b128 v[202:205], v168 offset:51200
	ds_read_b128 v[206:209], v168 offset:52224
	ds_read_b128 v[210:213], v168 offset:53248
	ds_read_b128 v[214:217], v168 offset:54272
	ds_read_b128 v[218:221], v168 offset:55296
	ds_read_b128 v[222:225], v168 offset:56320
	global_load_lds_dwordx4 v[174:175], off
	s_mov_b32 m0, s29
	v_lshl_add_u64 v[174:175], v[244:245], 0, s[88:89]
	global_load_lds_dwordx4 v[174:175], off
	s_barrier
; #define PG8_STAGE(bufoff, gbase) do { _Pragma("unroll") for (int _i = 0; _i < 2; ++_i) \
;         __builtin_amdgcn_global_load_lds((const unsigned*)((const char*)(gbase) + voff[_i]), (LAS unsigned*)(lds + (bufoff) + ldsw + _i * 8192), 16, 0, 0); } while (0)
; #define PG8_WAIT_V(n) asm volatile("s_waitcnt vmcnt(" #n ")" ::: "memory")
; #define PG8_WAIT_L(n) asm volatile("s_waitcnt lgkmcnt(" #n ")" ::: "memory")
; #define PG8_BAR __builtin_amdgcn_s_barrier()
; #define PG8_SCHED __builtin_amdgcn_sched_barrier(0)
;     ...
;             PG8_BAR; PG8_WAIT_L(0); PG8_MMA(1, 0, At, B0); PG8_BAR; PG8_SCHED;
;             PG8_STAGE(PG8_SB(1, 1), b3 + hstep);
;             PG8_WAIT_V(6); PG8_BAR; PG8_MMA(1, 1, At, B1); PG8_BAR;
;         }
;         E(acc, cur.pm + pm0, cur.pn, wr, wc, fr, fq);
;     __device__ __forceinline__ void operator()(Acc& acc, int pm, int pn, int wr, int wc, int fr, int fq) const {
;         const int brow = pm * 256;
;         const bool lat = brow < T_LAT;
;         const float* xin = lat ? xin_lat : xin_ctx;
;         float* xout = lat ? xout_lat : xout_ctx;
;         const int rsub = lat ? 0 : T_LAT;
;         const int mi = lat ? (brow >> 12) : 8;
;         const int c0 = pn * 256 + wc * 32 + fq * 4;
;         const float* gp = modv_l + (size_t)mi * 6144 + gate_i * 1024 + c0;
; #pragma unroll
;         for (int bj = 0; bj < 2; ++bj)
; #pragma unroll
;             for (int n = 0; n < 2; ++n) {
;                 const f32x4 gv = *reinterpret_cast<const f32x4*>(gp + bj * 128 + n * 16);
; #pragma unroll
;                 for (int ai = 0; ai < 2; ++ai)
; #pragma unroll
;                     for (int m = 0; m < 4; ++m) {
;                         const size_t o = (size_t)(brow + ai * 128 + wr * 64 + m * 16 + fr - rsub) * DM + c0 + bj * 128 + n * 16;
;                         const f32x4 xi = *reinterpret_cast<const f32x4*>(xin + o);
;                         const f32x4 a = acc[ai][bj][m][n];
;                         f32x4 r = {xi[0] + gv[0] * a[0], xi[1] + gv[1] * a[1], xi[2] + gv[2] * a[2], xi[3] + gv[3] * a[3]};
;                         *reinterpret_cast<f32x4*>(xout + o) = r;
;                     }
	s_waitcnt lgkmcnt(0)
	s_setprio 1
	v_mfma_f32_16x16x32_bf16 v[110:113], v[130:133], v[194:197], v[110:113]
	v_mfma_f32_16x16x32_bf16 v[78:81], v[162:165], v[194:197], v[78:81]
	v_mfma_f32_16x16x32_bf16 v[106:109], v[130:133], v[202:205], v[106:109]
	v_mfma_f32_16x16x32_bf16 v[70:73], v[162:165], v[202:205], v[70:73]
	v_mfma_f32_16x16x32_bf16 v[102:105], v[130:133], v[210:213], v[102:105]
	v_mfma_f32_16x16x32_bf16 v[62:65], v[162:165], v[210:213], v[62:65]
	v_mfma_f32_16x16x32_bf16 v[86:89], v[130:133], v[218:221], v[86:89]
	v_mfma_f32_16x16x32_bf16 v[54:57], v[162:165], v[218:221], v[54:57]
	v_mfma_f32_16x16x32_bf16 v[110:113], v[158:161], v[198:201], v[110:113]
	v_mfma_f32_16x16x32_bf16 v[78:81], v[170:173], v[198:201], v[78:81]
	v_mfma_f32_16x16x32_bf16 v[106:109], v[158:161], v[206:209], v[106:109]
	v_mfma_f32_16x16x32_bf16 v[70:73], v[170:173], v[206:209], v[70:73]
	v_mfma_f32_16x16x32_bf16 v[102:105], v[158:161], v[214:217], v[102:105]
	v_mfma_f32_16x16x32_bf16 v[62:65], v[170:173], v[214:217], v[62:65]
	v_mfma_f32_16x16x32_bf16 v[86:89], v[158:161], v[222:225], v[86:89]
	v_mfma_f32_16x16x32_bf16 v[54:57], v[170:173], v[222:225], v[54:57]
	s_setprio 0
	s_barrier
	s_add_i32 s0, s0, s18
	s_mov_b32 m0, s0
	v_lshl_add_u64 v[130:131], v[246:247], 0, s[88:89]
	global_load_lds_dwordx4 v[130:131], off
	s_add_i32 m0, s0, 0x2000
	v_lshl_add_u64 v[130:131], v[248:249], 0, s[88:89]
	global_load_lds_dwordx4 v[130:131], off
	s_waitcnt vmcnt(6)
	s_barrier
	s_setprio 1
	v_mfma_f32_16x16x32_bf16 v[42:45], v[226:229], v[194:197], v[42:45]
	v_mfma_f32_16x16x32_bf16 v[14:17], v[234:237], v[194:197], v[14:17]
	v_mfma_f32_16x16x32_bf16 v[34:37], v[226:229], v[202:205], v[34:37]
	v_mfma_f32_16x16x32_bf16 v[10:13], v[234:237], v[202:205], v[10:13]
	v_mfma_f32_16x16x32_bf16 v[26:29], v[226:229], v[210:213], v[26:29]
	v_mfma_f32_16x16x32_bf16 v[6:9], v[234:237], v[210:213], v[6:9]
	v_mfma_f32_16x16x32_bf16 v[18:21], v[226:229], v[218:221], v[18:21]
	v_mfma_f32_16x16x32_bf16 v[2:5], v[234:237], v[218:221], v[2:5]
	v_mfma_f32_16x16x32_bf16 v[42:45], v[230:233], v[198:201], v[42:45]
	v_mfma_f32_16x16x32_bf16 v[14:17], v[238:241], v[198:201], v[14:17]
	v_mfma_f32_16x16x32_bf16 v[34:37], v[230:233], v[206:209], v[34:37]
	v_mfma_f32_16x16x32_bf16 v[10:13], v[238:241], v[206:209], v[10:13]
	v_mfma_f32_16x16x32_bf16 v[26:29], v[230:233], v[214:217], v[26:29]
	v_mfma_f32_16x16x32_bf16 v[6:9], v[238:241], v[214:217], v[6:9]
	v_mfma_f32_16x16x32_bf16 v[18:21], v[230:233], v[222:225], v[18:21]
	v_mfma_f32_16x16x32_bf16 v[2:5], v[238:241], v[222:225], v[2:5]
	s_setprio 0
	s_add_u32 s40, s40, 0x100
	s_addc_u32 s41, s41, 0
	s_add_u32 s58, s58, 0x100
	s_addc_u32 s59, s59, 0
	s_cmp_ge_u32 s67, s7
	s_mov_b32 s46, s67
	s_barrier
	s_cbranch_scc0 .LBB0_1245
	s_lshl_b32 s48, s65, 8
	v_readlane_b32 s0, v255, 26
	v_readlane_b32 s40, v255, 24
	v_readlane_b32 s68, v254, 6
	s_cmpk_lt_i32 s65, 0x80
	v_readlane_b32 s1, v255, 27
	v_readlane_b32 s41, v255, 25
	v_readlane_b32 s70, v254, 8
	v_readlane_b32 s71, v254, 9
	v_readlane_b32 s72, v254, 10
	v_readlane_b32 s73, v254, 11
	s_cselect_b32 s47, s41, s1
	s_cselect_b32 s46, s40, s0
	s_cselect_b32 s49, 0, 0xffff8000
	s_cselect_b32 s41, s71, s73
	s_cselect_b32 s40, s70, s72
	s_min_i32 s0, s65, 0x80
	s_ashr_i32 s0, s0, 4
	s_mul_hi_i32 s1, s0, 0x6000
	s_mulk_i32 s0, 0x6000
	s_add_u32 s0, s50, s0
	s_addc_u32 s1, s51, s1
	s_add_i32 s49, s49, s48
	s_add_u32 s0, s0, 0x2000
	s_addc_u32 s1, s1, 0
	v_lshl_or_b32 v162, s66, 8, v167
	v_add_u32_e32 v164, s49, v1
	v_ashrrev_i32_e32 v163, 31, v162
	v_lshl_add_u64 v[174:175], v[162:163], 2, s[0:1]
	global_load_dwordx4 v[130:133], v[174:175], off
	global_load_dwordx4 v[158:161], v[174:175], off offset:64
	global_load_dwordx4 v[170:173], v[174:175], off offset:512
	global_load_dwordx4 v[192:195], v[174:175], off offset:576
	v_lshl_add_u32 v165, v164, 10, v162
	v_lshlrev_b32_e32 v165, 2, v165
	v_add_u32_e32 v169, 0x10000, v165
	v_add_u32_e32 v248, 0x20000, v165
	v_add_u32_e32 v162, 0x30000, v165
	v_add_u32_e32 v163, 0x80000, v165
	v_add_u32_e32 v164, 0x90000, v165
	v_add_u32_e32 v174, 0xa0000, v165
	v_add_u32_e32 v175, 0xb0000, v165
	global_load_dwordx4 v[196:199], v165, s[46:47]
	global_load_dwordx4 v[200:203], v165, s[46:47] offset:64
	global_load_dwordx4 v[204:207], v169, s[46:47]
	global_load_dwordx4 v[208:211], v169, s[46:47] offset:64
	global_load_dwordx4 v[212:215], v248, s[46:47]
	global_load_dwordx4 v[216:219], v248, s[46:47] offset:64
	global_load_dwordx4 v[220:223], v162, s[46:47]
	global_load_dwordx4 v[224:227], v162, s[46:47] offset:64
	global_load_dwordx4 v[228:231], v163, s[46:47]
	global_load_dwordx4 v[232:235], v163, s[46:47] offset:64
	global_load_dwordx4 v[236:239], v164, s[46:47]
	global_load_dwordx4 v[240:243], v164, s[46:47] offset:64
	global_load_dwordx4 v[244:247], v174, s[46:47]
	v_readlane_b32 s74, v254, 12
	v_readlane_b32 s75, v254, 13
	v_readlane_b32 s74, v255, 22
	s_and_b64 vcc, exec, s[44:45]
	s_mov_b32 s66, s62
	s_mov_b32 s65, s64
	s_mov_b64 s[58:59], s[14:15]
	s_mov_b32 s94, 0x87ff
	v_readlane_b32 s75, v255, 23
	v_readlane_b32 s69, v254, 7
	s_waitcnt vmcnt(12)
	v_pk_fma_f32 v[126:127], v[126:127], v[130:131], v[196:197]
	v_pk_fma_f32 v[128:129], v[128:129], v[132:133], v[198:199]
	global_store_dwordx4 v165, v[126:129], s[40:41]
	global_load_dwordx4 v[196:199], v174, s[46:47] offset:64
	s_waitcnt vmcnt(13)
	v_pk_fma_f32 v[98:99], v[98:99], v[158:159], v[200:201]
	v_pk_fma_f32 v[100:101], v[100:101], v[160:161], v[202:203]
	global_store_dwordx4 v165, v[98:101], s[40:41] offset:64
	global_load_dwordx4 v[200:203], v175, s[46:47]
	s_waitcnt vmcnt(14)
;     __device__ __forceinline__ void operator()(Acc& acc, int pm, int pn, int wr, int wc, int fr, int fq) const {
;     ...
; #pragma unroll
;         for (int bj = 0; bj < 2; ++bj)
; #pragma unroll
;             for (int n = 0; n < 2; ++n) {
;                 const f32x4 gv = *reinterpret_cast<const f32x4*>(gp + bj * 128 + n * 16);
; #pragma unroll
;                 for (int ai = 0; ai < 2; ++ai)
; #pragma unroll
;                     for (int m = 0; m < 4; ++m) {
;                         const size_t o = (size_t)(brow + ai * 128 + wr * 64 + m * 16 + fr - rsub) * DM + c0 + bj * 128 + n * 16;
;                         const f32x4 xi = *reinterpret_cast<const f32x4*>(xin + o);
;                         const f32x4 a = acc[ai][bj][m][n];
;                         f32x4 r = {xi[0] + gv[0] * a[0], xi[1] + gv[1] * a[1], xi[2] + gv[2] * a[2], xi[3] + gv[3] * a[3]};
;                         *reinterpret_cast<f32x4*>(xout + o) = r;
;                     }
	v_pk_fma_f32 v[122:123], v[122:123], v[130:131], v[204:205]
	v_pk_fma_f32 v[124:125], v[124:125], v[132:133], v[206:207]
	global_store_dwordx4 v169, v[122:125], s[40:41]
	global_load_dwordx4 v[204:207], v175, s[46:47] offset:64
	s_waitcnt vmcnt(15)
	v_pk_fma_f32 v[94:95], v[94:95], v[158:159], v[208:209]
	v_pk_fma_f32 v[96:97], v[96:97], v[160:161], v[210:211]
	global_store_dwordx4 v169, v[94:97], s[40:41] offset:64
	global_load_dwordx4 v[208:211], v165, s[46:47] offset:512
	s_waitcnt vmcnt(16)
	v_pk_fma_f32 v[118:119], v[118:119], v[130:131], v[212:213]
	v_pk_fma_f32 v[120:121], v[120:121], v[132:133], v[214:215]
	global_store_dwordx4 v248, v[118:121], s[40:41]
	global_load_dwordx4 v[212:215], v165, s[46:47] offset:576
	s_waitcnt vmcnt(17)
	v_pk_fma_f32 v[90:91], v[90:91], v[158:159], v[216:217]
	v_pk_fma_f32 v[92:93], v[92:93], v[160:161], v[218:219]
	global_store_dwordx4 v248, v[90:93], s[40:41] offset:64
	global_load_dwordx4 v[216:219], v169, s[46:47] offset:512
	s_waitcnt vmcnt(18)
	v_pk_fma_f32 v[114:115], v[114:115], v[130:131], v[220:221]
	v_pk_fma_f32 v[116:117], v[116:117], v[132:133], v[222:223]
	global_store_dwordx4 v162, v[114:117], s[40:41]
	global_load_dwordx4 v[220:223], v169, s[46:47] offset:576
	s_waitcnt vmcnt(19)
	v_pk_fma_f32 v[82:83], v[82:83], v[158:159], v[224:225]
	v_pk_fma_f32 v[84:85], v[84:85], v[160:161], v[226:227]
	global_store_dwordx4 v162, v[82:85], s[40:41] offset:64
	global_load_dwordx4 v[224:227], v248, s[46:47] offset:512
	s_waitcnt vmcnt(20)
	v_pk_fma_f32 v[110:111], v[110:111], v[130:131], v[228:229]
	v_pk_fma_f32 v[112:113], v[112:113], v[132:133], v[230:231]
	global_store_dwordx4 v163, v[110:113], s[40:41]
	global_load_dwordx4 v[228:231], v248, s[46:47] offset:576
	s_waitcnt vmcnt(21)
	v_pk_fma_f32 v[78:79], v[78:79], v[158:159], v[232:233]
	v_pk_fma_f32 v[80:81], v[80:81], v[160:161], v[234:235]
	global_store_dwordx4 v163, v[78:81], s[40:41] offset:64
	global_load_dwordx4 v[232:235], v162, s[46:47] offset:512
	s_waitcnt vmcnt(22)
	v_pk_fma_f32 v[106:107], v[106:107], v[130:131], v[236:237]
	v_pk_fma_f32 v[108:109], v[108:109], v[132:133], v[238:239]
	global_store_dwordx4 v164, v[106:109], s[40:41]
	global_load_dwordx4 v[236:239], v162, s[46:47] offset:576
	s_waitcnt vmcnt(23)
	v_pk_fma_f32 v[70:71], v[70:71], v[158:159], v[240:241]
	v_pk_fma_f32 v[72:73], v[72:73], v[160:161], v[242:243]
	global_store_dwordx4 v164, v[70:73], s[40:41] offset:64
	global_load_dwordx4 v[240:243], v163, s[46:47] offset:512
	s_waitcnt vmcnt(24)
	v_pk_fma_f32 v[102:103], v[102:103], v[130:131], v[244:245]
	v_pk_fma_f32 v[104:105], v[104:105], v[132:133], v[246:247]
	global_store_dwordx4 v174, v[102:105], s[40:41]
	global_load_dwordx4 v[244:247], v163, s[46:47] offset:576
	s_waitcnt vmcnt(24)
	v_pk_fma_f32 v[62:63], v[62:63], v[158:159], v[196:197]
	v_pk_fma_f32 v[64:65], v[64:65], v[160:161], v[198:199]
	global_store_dwordx4 v174, v[62:65], s[40:41] offset:64
	global_load_dwordx4 v[196:199], v164, s[46:47] offset:512
	s_waitcnt vmcnt(24)
	v_pk_fma_f32 v[86:87], v[86:87], v[130:131], v[200:201]
	v_pk_fma_f32 v[88:89], v[88:89], v[132:133], v[202:203]
	global_store_dwordx4 v175, v[86:89], s[40:41]
	global_load_dwordx4 v[200:203], v164, s[46:47] offset:576
	s_waitcnt vmcnt(24)
	v_pk_fma_f32 v[54:55], v[54:55], v[158:159], v[204:205]
	v_pk_fma_f32 v[56:57], v[56:57], v[160:161], v[206:207]
	global_store_dwordx4 v175, v[54:57], s[40:41] offset:64
	global_load_dwordx4 v[204:207], v174, s[46:47] offset:512
	s_waitcnt vmcnt(24)
	v_pk_fma_f32 v[74:75], v[74:75], v[170:171], v[208:209]
	v_pk_fma_f32 v[76:77], v[76:77], v[172:173], v[210:211]
	global_store_dwordx4 v165, v[74:77], s[40:41] offset:512
	global_load_dwordx4 v[208:211], v174, s[46:47] offset:576
	s_waitcnt vmcnt(24)
	v_pk_fma_f32 v[46:47], v[46:47], v[192:193], v[212:213]
	v_pk_fma_f32 v[48:49], v[48:49], v[194:195], v[214:215]
	global_store_dwordx4 v165, v[46:49], s[40:41] offset:576
	global_load_dwordx4 v[212:215], v175, s[46:47] offset:512
	s_waitcnt vmcnt(24)
	v_pk_fma_f32 v[66:67], v[66:67], v[170:171], v[216:217]
	v_pk_fma_f32 v[68:69], v[68:69], v[172:173], v[218:219]
	global_store_dwordx4 v169, v[66:69], s[40:41] offset:512
	global_load_dwordx4 v[216:219], v175, s[46:47] offset:576
	s_waitcnt vmcnt(24)
	v_pk_fma_f32 v[38:39], v[38:39], v[192:193], v[220:221]
	v_pk_fma_f32 v[40:41], v[40:41], v[194:195], v[222:223]
	global_store_dwordx4 v169, v[38:41], s[40:41] offset:576
	s_waitcnt vmcnt(23)
	v_pk_fma_f32 v[58:59], v[58:59], v[170:171], v[224:225]
	v_pk_fma_f32 v[60:61], v[60:61], v[172:173], v[226:227]
	global_store_dwordx4 v248, v[58:61], s[40:41] offset:512
	s_waitcnt vmcnt(22)
	v_pk_fma_f32 v[30:31], v[30:31], v[192:193], v[228:229]
	v_pk_fma_f32 v[32:33], v[32:33], v[194:195], v[230:231]
	global_store_dwordx4 v248, v[30:33], s[40:41] offset:576
	s_waitcnt vmcnt(21)
	v_pk_fma_f32 v[50:51], v[50:51], v[170:171], v[232:233]
	v_pk_fma_f32 v[52:53], v[52:53], v[172:173], v[234:235]
	global_store_dwordx4 v162, v[50:53], s[40:41] offset:512
	s_waitcnt vmcnt(20)
	v_pk_fma_f32 v[22:23], v[22:23], v[192:193], v[236:237]
	v_pk_fma_f32 v[24:25], v[24:25], v[194:195], v[238:239]
	global_store_dwordx4 v162, v[22:25], s[40:41] offset:576
	s_waitcnt vmcnt(19)
	v_pk_fma_f32 v[42:43], v[42:43], v[170:171], v[240:241]
	v_pk_fma_f32 v[44:45], v[44:45], v[172:173], v[242:243]
	global_store_dwordx4 v163, v[42:45], s[40:41] offset:512
	s_waitcnt vmcnt(18)
	v_pk_fma_f32 v[14:15], v[14:15], v[192:193], v[244:245]
	v_pk_fma_f32 v[16:17], v[16:17], v[194:195], v[246:247]
	global_store_dwordx4 v163, v[14:17], s[40:41] offset:576
	s_waitcnt vmcnt(17)
	v_pk_fma_f32 v[34:35], v[34:35], v[170:171], v[196:197]
	v_pk_fma_f32 v[36:37], v[36:37], v[172:173], v[198:199]
	global_store_dwordx4 v164, v[34:37], s[40:41] offset:512
	s_waitcnt vmcnt(16)
	v_pk_fma_f32 v[10:11], v[10:11], v[192:193], v[200:201]
	v_pk_fma_f32 v[12:13], v[12:13], v[194:195], v[202:203]
	global_store_dwordx4 v164, v[10:13], s[40:41] offset:576
	s_waitcnt vmcnt(15)
	v_pk_fma_f32 v[26:27], v[26:27], v[170:171], v[204:205]
	v_pk_fma_f32 v[28:29], v[28:29], v[172:173], v[206:207]
	global_store_dwordx4 v174, v[26:29], s[40:41] offset:512
	s_waitcnt vmcnt(14)
	v_pk_fma_f32 v[6:7], v[6:7], v[192:193], v[208:209]
	v_pk_fma_f32 v[8:9], v[8:9], v[194:195], v[210:211]
	global_store_dwordx4 v174, v[6:9], s[40:41] offset:576
	s_waitcnt vmcnt(13)
	v_pk_fma_f32 v[18:19], v[18:19], v[170:171], v[212:213]
	v_pk_fma_f32 v[20:21], v[20:21], v[172:173], v[214:215]
	global_store_dwordx4 v175, v[18:21], s[40:41] offset:512
	s_waitcnt vmcnt(12)
	v_pk_fma_f32 v[2:3], v[2:3], v[192:193], v[216:217]
	v_pk_fma_f32 v[4:5], v[4:5], v[194:195], v[218:219]
	global_store_dwordx4 v175, v[2:5], s[40:41] offset:576
	s_mov_b64 s[40:41], s[12:13]
	s_mov_b64 s[0:1], 0x2000
	s_cbranch_vccz .LBB0_1238
	s_waitcnt vmcnt(0)
	s_cmpk_gt_u32 s4, 0xff
	s_cbranch_scc1 .LBB0_1249
	s_barrier

; #define PG8_STAGE(bufoff, gbase) do { _Pragma("unroll") for (int _i = 0; _i < 2; ++_i) \
;         __builtin_amdgcn_global_load_lds((const unsigned*)((const char*)(gbase) + voff[_i]), (LAS unsigned*)(lds + (bufoff) + ldsw + _i * 8192), 16, 0, 0); } while (0)
; #define PG8_LDA(dst, b, h) do { _Pragma("unroll") for (int m = 0; m < 4; ++m) _Pragma("unroll") for (int k = 0; k < 2; ++k) dst[m][k] = *(const LAS bf16x8*)(lds + PG8_SA(b, h) + aoff + m * 2048 + k * 1024); } while (0)
; #define PG8_LDB(dst, b, h) do { _Pragma("unroll") for (int n = 0; n < 2; ++n) _Pragma("unroll") for (int k = 0; k < 2; ++k) dst[n][k] = *(const LAS bf16x8*)(lds + PG8_SB(b, h) + boff + n * 2048 + k * 1024); } while (0)
; #define PG8_WAIT_V(n) asm volatile("s_waitcnt vmcnt(" #n ")" ::: "memory")
; #define PG8_WAIT_L(n) asm volatile("s_waitcnt lgkmcnt(" #n ")" ::: "memory")
; #define PG8_BAR __builtin_amdgcn_s_barrier()
; #define PG8_SCHED __builtin_amdgcn_sched_barrier(0)
;     ...
;             PG8_LDB(B0, 0, 0); PG8_SCHED; PG8_LDA(At, 0, 0); PG8_STAGE(PG8_SA(1, 1), a1 + hstep);
;             PG8_WAIT_L(8); PG8_BAR; PG8_WAIT_L(0); PG8_MMA(0, 0, At, B0); PG8_BAR; PG8_SCHED;
;             PG8_LDB(B1, 0, 1); PG8_STAGE(PG8_SB(0, 0), b2);
;             PG8_BAR; PG8_WAIT_L(0); PG8_MMA(0, 1, At, B1); PG8_BAR;
;             PG8_LDA(At, 0, 1); PG8_STAGE(PG8_SA(0, 0), a2);
;             PG8_BAR; PG8_WAIT_L(0); PG8_MMA(1, 0, At, B0); PG8_BAR; PG8_SCHED;
;             PG8_STAGE(PG8_SB(0, 1), b2 + hstep);
;             PG8_WAIT_V(6); PG8_BAR; PG8_MMA(1, 1, At, B1); PG8_BAR;
.LBB0_1408:
	s_add_i32 s31, s5, 2
	s_add_u32 s0, s14, 0x80
	s_addc_u32 s1, s15, 0
	s_cmp_lg_u32 s30, s5
	s_cselect_b32 s0, s0, 0
	s_cselect_b32 s1, s1, 0
	s_add_u32 s40, s12, s0
	s_addc_u32 s41, s13, s1
	s_add_i32 s5, 0, 0x10000
	v_add_u32_e32 v157, s5, v155
	ds_read_b128 v[158:161], v157
	ds_read_b128 v[162:165], v157 offset:1024
	ds_read_b128 v[166:169], v157 offset:2048
	ds_read_b128 v[170:173], v157 offset:3072
	s_add_u32 s44, s10, s0
	s_addc_u32 s45, s11, s1
	v_lshl_add_u64 v[174:175], v[150:151], 0, s[14:15]
	s_add_i32 m0, s17, 0xc000
	ds_read_b128 v[194:197], v156
	ds_read_b128 v[198:201], v156 offset:1024
	ds_read_b128 v[202:205], v156 offset:2048
	ds_read_b128 v[206:209], v156 offset:3072
	ds_read_b128 v[210:213], v156 offset:4096
	ds_read_b128 v[214:217], v156 offset:5120
	ds_read_b128 v[218:221], v156 offset:6144
	ds_read_b128 v[222:225], v156 offset:7168
	global_load_lds_dwordx4 v[174:175], off
	s_add_i32 m0, s17, 0xe000
	v_lshl_add_u64 v[174:175], v[152:153], 0, s[14:15]
	global_load_lds_dwordx4 v[174:175], off
	s_waitcnt lgkmcnt(8)
	s_barrier
	s_waitcnt lgkmcnt(0)
	s_setprio 1
	v_mfma_f32_16x16x32_bf16 v[126:129], v[158:161], v[194:197], v[126:129]
	v_mfma_f32_16x16x32_bf16 v[98:101], v[166:169], v[194:197], v[98:101]
	v_mfma_f32_16x16x32_bf16 v[122:125], v[158:161], v[202:205], v[122:125]
	v_mfma_f32_16x16x32_bf16 v[94:97], v[166:169], v[202:205], v[94:97]
	v_mfma_f32_16x16x32_bf16 v[118:121], v[158:161], v[210:213], v[118:121]
	v_mfma_f32_16x16x32_bf16 v[90:93], v[166:169], v[210:213], v[90:93]
	v_mfma_f32_16x16x32_bf16 v[114:117], v[158:161], v[218:221], v[114:117]
	v_mfma_f32_16x16x32_bf16 v[82:85], v[166:169], v[218:221], v[82:85]
	v_mfma_f32_16x16x32_bf16 v[126:129], v[162:165], v[198:201], v[126:129]
	v_mfma_f32_16x16x32_bf16 v[98:101], v[170:173], v[198:201], v[98:101]
	v_mfma_f32_16x16x32_bf16 v[122:125], v[162:165], v[206:209], v[122:125]
	v_mfma_f32_16x16x32_bf16 v[94:97], v[170:173], v[206:209], v[94:97]
	v_mfma_f32_16x16x32_bf16 v[118:121], v[162:165], v[214:217], v[118:121]
	v_mfma_f32_16x16x32_bf16 v[90:93], v[170:173], v[214:217], v[90:93]
	v_mfma_f32_16x16x32_bf16 v[114:117], v[162:165], v[222:225], v[114:117]
	v_mfma_f32_16x16x32_bf16 v[82:85], v[170:173], v[222:225], v[82:85]
	s_setprio 0
	s_barrier
	s_add_i32 s36, 0, 0x14000
	s_add_i32 s0, s5, s16
	v_add_u32_e32 v157, s36, v155
	v_lshl_add_u64 v[174:175], s[44:45], 0, v[130:131]
	s_mov_b32 m0, s0
	ds_read_b128 v[226:229], v157
	ds_read_b128 v[230:233], v157 offset:1024
	ds_read_b128 v[234:237], v157 offset:2048
	ds_read_b128 v[238:241], v157 offset:3072
	global_load_lds_dwordx4 v[174:175], off
	s_add_i32 m0, s0, 0x2000
	v_lshl_add_u64 v[192:193], s[44:45], 0, v[132:133]
	global_load_lds_dwordx4 v[192:193], off
	s_barrier
	s_waitcnt lgkmcnt(0)
	s_setprio 1
	v_mfma_f32_16x16x32_bf16 v[74:77], v[226:229], v[194:197], v[74:77]
	v_mfma_f32_16x16x32_bf16 v[46:49], v[234:237], v[194:197], v[46:49]
	v_mfma_f32_16x16x32_bf16 v[66:69], v[226:229], v[202:205], v[66:69]
	v_mfma_f32_16x16x32_bf16 v[38:41], v[234:237], v[202:205], v[38:41]
	v_mfma_f32_16x16x32_bf16 v[58:61], v[226:229], v[210:213], v[58:61]
	v_mfma_f32_16x16x32_bf16 v[30:33], v[234:237], v[210:213], v[30:33]
	v_mfma_f32_16x16x32_bf16 v[50:53], v[226:229], v[218:221], v[50:53]
	v_mfma_f32_16x16x32_bf16 v[22:25], v[234:237], v[218:221], v[22:25]
	v_mfma_f32_16x16x32_bf16 v[74:77], v[230:233], v[198:201], v[74:77]
	v_mfma_f32_16x16x32_bf16 v[46:49], v[238:241], v[198:201], v[46:49]
	v_mfma_f32_16x16x32_bf16 v[66:69], v[230:233], v[206:209], v[66:69]
	v_mfma_f32_16x16x32_bf16 v[38:41], v[238:241], v[206:209], v[38:41]
	v_mfma_f32_16x16x32_bf16 v[58:61], v[230:233], v[214:217], v[58:61]
	v_mfma_f32_16x16x32_bf16 v[30:33], v[238:241], v[214:217], v[30:33]
	v_mfma_f32_16x16x32_bf16 v[50:53], v[230:233], v[222:225], v[50:53]
	v_mfma_f32_16x16x32_bf16 v[22:25], v[238:241], v[222:225], v[22:25]
	s_setprio 0
	s_mov_b32 m0, s17
	v_lshl_add_u64 v[242:243], s[40:41], 0, v[130:131]
	s_barrier
	ds_read_b128 v[194:197], v156 offset:16384
	ds_read_b128 v[198:201], v156 offset:17408
	ds_read_b128 v[202:205], v156 offset:18432
	ds_read_b128 v[206:209], v156 offset:19456
	ds_read_b128 v[210:213], v156 offset:20480
	ds_read_b128 v[214:217], v156 offset:21504
	ds_read_b128 v[218:221], v156 offset:22528
	ds_read_b128 v[222:225], v156 offset:23552
	global_load_lds_dwordx4 v[242:243], off
	s_mov_b32 m0, s18
	v_lshl_add_u64 v[244:245], s[40:41], 0, v[132:133]
	global_load_lds_dwordx4 v[244:245], off
	s_barrier
	s_waitcnt lgkmcnt(0)
	s_setprio 1
	v_mfma_f32_16x16x32_bf16 v[110:113], v[158:161], v[194:197], v[110:113]
	v_mfma_f32_16x16x32_bf16 v[78:81], v[166:169], v[194:197], v[78:81]
	v_mfma_f32_16x16x32_bf16 v[106:109], v[158:161], v[202:205], v[106:109]
	v_mfma_f32_16x16x32_bf16 v[70:73], v[166:169], v[202:205], v[70:73]
	v_mfma_f32_16x16x32_bf16 v[102:105], v[158:161], v[210:213], v[102:105]
	v_mfma_f32_16x16x32_bf16 v[62:65], v[166:169], v[210:213], v[62:65]
	v_mfma_f32_16x16x32_bf16 v[86:89], v[158:161], v[218:221], v[86:89]
	v_mfma_f32_16x16x32_bf16 v[54:57], v[166:169], v[218:221], v[54:57]
	v_mfma_f32_16x16x32_bf16 v[110:113], v[162:165], v[198:201], v[110:113]
	v_mfma_f32_16x16x32_bf16 v[78:81], v[170:173], v[198:201], v[78:81]
	v_mfma_f32_16x16x32_bf16 v[106:109], v[162:165], v[206:209], v[106:109]
	v_mfma_f32_16x16x32_bf16 v[70:73], v[170:173], v[206:209], v[70:73]
	v_mfma_f32_16x16x32_bf16 v[102:105], v[162:165], v[214:217], v[102:105]
	v_mfma_f32_16x16x32_bf16 v[62:65], v[170:173], v[214:217], v[62:65]
	v_mfma_f32_16x16x32_bf16 v[86:89], v[162:165], v[222:225], v[86:89]
	v_mfma_f32_16x16x32_bf16 v[54:57], v[170:173], v[222:225], v[54:57]
	s_setprio 0
	s_barrier
; #define PG8_STAGE(bufoff, gbase) do { _Pragma("unroll") for (int _i = 0; _i < 2; ++_i) \
;         __builtin_amdgcn_global_load_lds((const unsigned*)((const char*)(gbase) + voff[_i]), (LAS unsigned*)(lds + (bufoff) + ldsw + _i * 8192), 16, 0, 0); } while (0)
; #define PG8_LDA(dst, b, h) do { _Pragma("unroll") for (int m = 0; m < 4; ++m) _Pragma("unroll") for (int k = 0; k < 2; ++k) dst[m][k] = *(const LAS bf16x8*)(lds + PG8_SA(b, h) + aoff + m * 2048 + k * 1024); } while (0)
; #define PG8_LDB(dst, b, h) do { _Pragma("unroll") for (int n = 0; n < 2; ++n) _Pragma("unroll") for (int k = 0; k < 2; ++k) dst[n][k] = *(const LAS bf16x8*)(lds + PG8_SB(b, h) + boff + n * 2048 + k * 1024); } while (0)
; #define PG8_WAIT_V(n) asm volatile("s_waitcnt vmcnt(" #n ")" ::: "memory")
; #define PG8_WAIT_L(n) asm volatile("s_waitcnt lgkmcnt(" #n ")" ::: "memory")
; #define PG8_BAR __builtin_amdgcn_s_barrier()
; #define PG8_SCHED __builtin_amdgcn_sched_barrier(0)
;     ...
;             PG8_WAIT_V(6); PG8_BAR; PG8_MMA(1, 1, At, B1); PG8_BAR;
;             PG8_LDB(B0, 1, 0); PG8_SCHED; PG8_LDA(At, 1, 0); PG8_STAGE(PG8_SA(0, 1), a2 + hstep);
;             PG8_WAIT_L(8); PG8_BAR; PG8_WAIT_L(0); PG8_MMA(0, 0, At, B0); PG8_BAR; PG8_SCHED;
;             PG8_LDB(B1, 1, 1); PG8_STAGE(PG8_SB(1, 0), b3);
;             PG8_BAR; PG8_WAIT_L(0); PG8_MMA(0, 1, At, B1); PG8_BAR;
;             PG8_LDA(At, 1, 1); PG8_STAGE(PG8_SA(1, 0), a3);
;             PG8_BAR; PG8_WAIT_L(0); PG8_MMA(1, 0, At, B0); PG8_BAR; PG8_SCHED;
	s_add_u32 s0, s44, s7
	s_addc_u32 s1, s45, 0
	s_add_i32 s5, s36, s16
	v_lshl_add_u64 v[246:247], s[0:1], 0, v[130:131]
	s_mov_b32 m0, s5
	v_lshl_add_u64 v[248:249], s[0:1], 0, v[132:133]
	global_load_lds_dwordx4 v[246:247], off
	s_add_i32 m0, s5, 0x2000
	s_nop 0
	global_load_lds_dwordx4 v[248:249], off
	s_waitcnt vmcnt(6)
	s_barrier
	s_setprio 1
	v_mfma_f32_16x16x32_bf16 v[42:45], v[226:229], v[194:197], v[42:45]
	v_mfma_f32_16x16x32_bf16 v[14:17], v[234:237], v[194:197], v[14:17]
	v_mfma_f32_16x16x32_bf16 v[34:37], v[226:229], v[202:205], v[34:37]
	v_mfma_f32_16x16x32_bf16 v[10:13], v[234:237], v[202:205], v[10:13]
	v_mfma_f32_16x16x32_bf16 v[26:29], v[226:229], v[210:213], v[26:29]
	v_mfma_f32_16x16x32_bf16 v[6:9], v[234:237], v[210:213], v[6:9]
	v_mfma_f32_16x16x32_bf16 v[18:21], v[226:229], v[218:221], v[18:21]
	v_mfma_f32_16x16x32_bf16 v[2:5], v[234:237], v[218:221], v[2:5]
	v_mfma_f32_16x16x32_bf16 v[42:45], v[230:233], v[198:201], v[42:45]
	v_mfma_f32_16x16x32_bf16 v[14:17], v[238:241], v[198:201], v[14:17]
	v_mfma_f32_16x16x32_bf16 v[34:37], v[230:233], v[206:209], v[34:37]
	v_mfma_f32_16x16x32_bf16 v[10:13], v[238:241], v[206:209], v[10:13]
	v_mfma_f32_16x16x32_bf16 v[26:29], v[230:233], v[214:217], v[26:29]
	v_mfma_f32_16x16x32_bf16 v[6:9], v[238:241], v[214:217], v[6:9]
	v_mfma_f32_16x16x32_bf16 v[18:21], v[230:233], v[222:225], v[18:21]
	v_mfma_f32_16x16x32_bf16 v[2:5], v[238:241], v[222:225], v[2:5]
	s_setprio 0
	s_add_i32 s5, 0, 0x18000
	v_add_u32_e32 v157, s5, v155
	s_barrier
	ds_read_b128 v[158:161], v157
	ds_read_b128 v[162:165], v157 offset:1024
	ds_read_b128 v[166:169], v157 offset:2048
	ds_read_b128 v[170:173], v157 offset:3072
	s_add_u32 s0, s40, s7
	s_addc_u32 s1, s41, 0
	s_mov_b32 m0, s19
	v_lshl_add_u64 v[226:227], s[0:1], 0, v[130:131]
	ds_read_b128 v[194:197], v156 offset:32768
	ds_read_b128 v[198:201], v156 offset:33792
	ds_read_b128 v[202:205], v156 offset:34816
	ds_read_b128 v[206:209], v156 offset:35840
	ds_read_b128 v[210:213], v156 offset:36864
	ds_read_b128 v[214:217], v156 offset:37888
	ds_read_b128 v[218:221], v156 offset:38912
	ds_read_b128 v[222:225], v156 offset:39936
	global_load_lds_dwordx4 v[226:227], off
	s_mov_b32 m0, s20
	v_lshl_add_u64 v[226:227], s[0:1], 0, v[132:133]
	global_load_lds_dwordx4 v[226:227], off
	s_waitcnt lgkmcnt(8)
	s_barrier
	s_waitcnt lgkmcnt(0)
	s_setprio 1
	v_mfma_f32_16x16x32_bf16 v[126:129], v[158:161], v[194:197], v[126:129]
	v_mfma_f32_16x16x32_bf16 v[98:101], v[166:169], v[194:197], v[98:101]
	v_mfma_f32_16x16x32_bf16 v[122:125], v[158:161], v[202:205], v[122:125]
	v_mfma_f32_16x16x32_bf16 v[94:97], v[166:169], v[202:205], v[94:97]
	v_mfma_f32_16x16x32_bf16 v[118:121], v[158:161], v[210:213], v[118:121]
	v_mfma_f32_16x16x32_bf16 v[90:93], v[166:169], v[210:213], v[90:93]
	v_mfma_f32_16x16x32_bf16 v[114:117], v[158:161], v[218:221], v[114:117]
	v_mfma_f32_16x16x32_bf16 v[82:85], v[166:169], v[218:221], v[82:85]
	v_mfma_f32_16x16x32_bf16 v[126:129], v[162:165], v[198:201], v[126:129]
	v_mfma_f32_16x16x32_bf16 v[98:101], v[170:173], v[198:201], v[98:101]
	v_mfma_f32_16x16x32_bf16 v[122:125], v[162:165], v[206:209], v[122:125]
	v_mfma_f32_16x16x32_bf16 v[94:97], v[170:173], v[206:209], v[94:97]
	v_mfma_f32_16x16x32_bf16 v[118:121], v[162:165], v[214:217], v[118:121]
	v_mfma_f32_16x16x32_bf16 v[90:93], v[170:173], v[214:217], v[90:93]
	v_mfma_f32_16x16x32_bf16 v[114:117], v[162:165], v[222:225], v[114:117]
	v_mfma_f32_16x16x32_bf16 v[82:85], v[170:173], v[222:225], v[82:85]
	s_setprio 0
	s_barrier
	s_add_i32 s0, 0, 0x1c000
	s_add_i32 s1, s5, s16
	v_add_u32_e32 v157, s0, v155
	v_lshl_add_u64 v[174:175], v[174:175], 0, s[88:89]
	s_mov_b32 m0, s1
	ds_read_b128 v[226:229], v157
	ds_read_b128 v[230:233], v157 offset:1024
	ds_read_b128 v[234:237], v157 offset:2048
	ds_read_b128 v[238:241], v157 offset:3072
	global_load_lds_dwordx4 v[174:175], off
	s_add_i32 m0, s1, 0x2000
	v_lshl_add_u64 v[174:175], v[192:193], 0, s[88:89]
	global_load_lds_dwordx4 v[174:175], off
	s_barrier
	s_waitcnt lgkmcnt(0)
	s_setprio 1
	v_mfma_f32_16x16x32_bf16 v[74:77], v[226:229], v[194:197], v[74:77]
	v_mfma_f32_16x16x32_bf16 v[46:49], v[234:237], v[194:197], v[46:49]
	v_mfma_f32_16x16x32_bf16 v[66:69], v[226:229], v[202:205], v[66:69]
	v_mfma_f32_16x16x32_bf16 v[38:41], v[234:237], v[202:205], v[38:41]
	v_mfma_f32_16x16x32_bf16 v[58:61], v[226:229], v[210:213], v[58:61]
	v_mfma_f32_16x16x32_bf16 v[30:33], v[234:237], v[210:213], v[30:33]
	v_mfma_f32_16x16x32_bf16 v[50:53], v[226:229], v[218:221], v[50:53]
	v_mfma_f32_16x16x32_bf16 v[22:25], v[234:237], v[218:221], v[22:25]
	v_mfma_f32_16x16x32_bf16 v[74:77], v[230:233], v[198:201], v[74:77]
	v_mfma_f32_16x16x32_bf16 v[46:49], v[238:241], v[198:201], v[46:49]
	v_mfma_f32_16x16x32_bf16 v[66:69], v[230:233], v[206:209], v[66:69]
	v_mfma_f32_16x16x32_bf16 v[38:41], v[238:241], v[206:209], v[38:41]
	v_mfma_f32_16x16x32_bf16 v[58:61], v[230:233], v[214:217], v[58:61]
	v_mfma_f32_16x16x32_bf16 v[30:33], v[238:241], v[214:217], v[30:33]
	v_mfma_f32_16x16x32_bf16 v[50:53], v[230:233], v[222:225], v[50:53]
	v_mfma_f32_16x16x32_bf16 v[22:25], v[238:241], v[222:225], v[22:25]
	s_setprio 0
	s_mov_b32 m0, s28
	v_lshl_add_u64 v[174:175], v[242:243], 0, s[88:89]
	s_barrier
	ds_read_b128 v[194:197], v156 offset:49152
	ds_read_b128 v[198:201], v156 offset:50176
	ds_read_b128 v[202:205], v156 offset:51200
	ds_read_b128 v[206:209], v156 offset:52224
	ds_read_b128 v[210:213], v156 offset:53248
	ds_read_b128 v[214:217], v156 offset:54272
	ds_read_b128 v[218:221], v156 offset:55296
	ds_read_b128 v[222:225], v156 offset:56320
	global_load_lds_dwordx4 v[174:175], off
	s_mov_b32 m0, s29
	v_lshl_add_u64 v[174:175], v[244:245], 0, s[88:89]
	global_load_lds_dwordx4 v[174:175], off
	s_barrier
; #define PG8_STAGE(bufoff, gbase) do { _Pragma("unroll") for (int _i = 0; _i < 2; ++_i) \
;         __builtin_amdgcn_global_load_lds((const unsigned*)((const char*)(gbase) + voff[_i]), (LAS unsigned*)(lds + (bufoff) + ldsw + _i * 8192), 16, 0, 0); } while (0)
; #define PG8_WAIT_V(n) asm volatile("s_waitcnt vmcnt(" #n ")" ::: "memory")
; #define PG8_WAIT_L(n) asm volatile("s_waitcnt lgkmcnt(" #n ")" ::: "memory")
; #define PG8_BAR __builtin_amdgcn_s_barrier()
; #define PG8_SCHED __builtin_amdgcn_sched_barrier(0)
;     ...
;             PG8_BAR; PG8_WAIT_L(0); PG8_MMA(1, 0, At, B0); PG8_BAR; PG8_SCHED;
;             PG8_STAGE(PG8_SB(1, 1), b3 + hstep);
;             PG8_WAIT_V(6); PG8_BAR; PG8_MMA(1, 1, At, B1); PG8_BAR;
;         }
;         E(acc, cur.pm + pm0, cur.pn, wr, wc, fr, fq);
;     __device__ __forceinline__ void operator()(Acc& acc, int pm, int pn, int wr, int wc, int fr, int fq) const {
;         const int brow = pm * 256;
;         const bool lat = brow < T_LAT;
;         const float* xin = lat ? xin_lat : xin_ctx;
;         float* xout = lat ? xout_lat : xout_ctx;
;         const int rsub = lat ? 0 : T_LAT;
;         const int mi = lat ? (brow >> 12) : 8;
;         const int c0 = pn * 256 + wc * 32 + fq * 4;
;         const float* gp = modv_l + (size_t)mi * 6144 + gate_i * 1024 + c0;
; #pragma unroll
;         for (int bj = 0; bj < 2; ++bj)
; #pragma unroll
;             for (int n = 0; n < 2; ++n) {
;                 const f32x4 gv = *reinterpret_cast<const f32x4*>(gp + bj * 128 + n * 16);
; #pragma unroll
;                 for (int ai = 0; ai < 2; ++ai)
; #pragma unroll
;                     for (int m = 0; m < 4; ++m) {
;                         const size_t o = (size_t)(brow + ai * 128 + wr * 64 + m * 16 + fr - rsub) * DM + c0 + bj * 128 + n * 16;
;                         const f32x4 xi = *reinterpret_cast<const f32x4*>(xin + o);
;                         const f32x4 a = acc[ai][bj][m][n];
;                         f32x4 r = {xi[0] + gv[0] * a[0], xi[1] + gv[1] * a[1], xi[2] + gv[2] * a[2], xi[3] + gv[3] * a[3]};
;                         *reinterpret_cast<f32x4*>(xout + o) = r;
;                     }
	s_waitcnt lgkmcnt(0)
	s_setprio 1
	v_mfma_f32_16x16x32_bf16 v[110:113], v[158:161], v[194:197], v[110:113]
	v_mfma_f32_16x16x32_bf16 v[78:81], v[166:169], v[194:197], v[78:81]
	v_mfma_f32_16x16x32_bf16 v[106:109], v[158:161], v[202:205], v[106:109]
	v_mfma_f32_16x16x32_bf16 v[70:73], v[166:169], v[202:205], v[70:73]
	v_mfma_f32_16x16x32_bf16 v[102:105], v[158:161], v[210:213], v[102:105]
	v_mfma_f32_16x16x32_bf16 v[62:65], v[166:169], v[210:213], v[62:65]
	v_mfma_f32_16x16x32_bf16 v[86:89], v[158:161], v[218:221], v[86:89]
	v_mfma_f32_16x16x32_bf16 v[54:57], v[166:169], v[218:221], v[54:57]
	v_mfma_f32_16x16x32_bf16 v[110:113], v[162:165], v[198:201], v[110:113]
	v_mfma_f32_16x16x32_bf16 v[78:81], v[170:173], v[198:201], v[78:81]
	v_mfma_f32_16x16x32_bf16 v[106:109], v[162:165], v[206:209], v[106:109]
	v_mfma_f32_16x16x32_bf16 v[70:73], v[170:173], v[206:209], v[70:73]
	v_mfma_f32_16x16x32_bf16 v[102:105], v[162:165], v[214:217], v[102:105]
	v_mfma_f32_16x16x32_bf16 v[62:65], v[170:173], v[214:217], v[62:65]
	v_mfma_f32_16x16x32_bf16 v[86:89], v[162:165], v[222:225], v[86:89]
	v_mfma_f32_16x16x32_bf16 v[54:57], v[170:173], v[222:225], v[54:57]
	s_setprio 0
	s_barrier
	s_add_i32 s0, s0, s16
	s_mov_b32 m0, s0
	v_lshl_add_u64 v[158:159], v[246:247], 0, s[88:89]
	global_load_lds_dwordx4 v[158:159], off
	s_add_i32 m0, s0, 0x2000
	v_lshl_add_u64 v[158:159], v[248:249], 0, s[88:89]
	global_load_lds_dwordx4 v[158:159], off
	s_waitcnt vmcnt(6)
	s_barrier
	s_setprio 1
	v_mfma_f32_16x16x32_bf16 v[42:45], v[226:229], v[194:197], v[42:45]
	v_mfma_f32_16x16x32_bf16 v[14:17], v[234:237], v[194:197], v[14:17]
	v_mfma_f32_16x16x32_bf16 v[34:37], v[226:229], v[202:205], v[34:37]
	v_mfma_f32_16x16x32_bf16 v[10:13], v[234:237], v[202:205], v[10:13]
	v_mfma_f32_16x16x32_bf16 v[26:29], v[226:229], v[210:213], v[26:29]
	v_mfma_f32_16x16x32_bf16 v[6:9], v[234:237], v[210:213], v[6:9]
	v_mfma_f32_16x16x32_bf16 v[18:21], v[226:229], v[218:221], v[18:21]
	v_mfma_f32_16x16x32_bf16 v[2:5], v[234:237], v[218:221], v[2:5]
	v_mfma_f32_16x16x32_bf16 v[42:45], v[230:233], v[198:201], v[42:45]
	v_mfma_f32_16x16x32_bf16 v[14:17], v[238:241], v[198:201], v[14:17]
	v_mfma_f32_16x16x32_bf16 v[34:37], v[230:233], v[206:209], v[34:37]
	v_mfma_f32_16x16x32_bf16 v[10:13], v[238:241], v[206:209], v[10:13]
	v_mfma_f32_16x16x32_bf16 v[26:29], v[230:233], v[214:217], v[26:29]
	v_mfma_f32_16x16x32_bf16 v[6:9], v[238:241], v[214:217], v[6:9]
	v_mfma_f32_16x16x32_bf16 v[18:21], v[230:233], v[222:225], v[18:21]
	v_mfma_f32_16x16x32_bf16 v[2:5], v[238:241], v[222:225], v[2:5]
	s_setprio 0
	s_add_u32 s14, s14, 0x100
	s_addc_u32 s15, s15, 0
	s_cmp_ge_u32 s31, s22
	s_mov_b32 s5, s31
	s_barrier
	s_cbranch_scc0 .LBB0_1408
	v_readlane_b32 s0, v253, 63
	v_readlane_b32 s10, v255, 26
	v_readlane_b32 s11, v255, 27
	v_readlane_b32 s12, v254, 6
	v_readlane_b32 s16, v254, 10
	v_readlane_b32 s17, v254, 11
	v_readlane_b32 s13, v254, 7
	v_readlane_b32 s14, v254, 8
	v_readlane_b32 s15, v254, 9
	v_readlane_b32 s18, v254, 12
	v_readlane_b32 s19, v254, 13
	v_mov_b32_e32 v161, v0
	v_lshl_or_b32 v157, v154, 2, s0
	v_or_b32_e32 v157, s23, v157
	v_lshlrev_b32_e32 v160, 2, v157
	v_readlane_b32 s0, v253, 61
	s_nop 1
	v_lshl_add_u64 v[158:159], s[50:51], 0, v[160:161]
	v_add_u32_e32 v162, s0, v1
	s_mov_b64 s[0:1], 0x32000
	v_lshl_add_u64 v[158:159], v[158:159], 0, s[0:1]
	global_load_dwordx4 v[192:195], v[158:159], off
	global_load_dwordx4 v[196:199], v[158:159], off offset:64
	global_load_dwordx4 v[200:203], v[158:159], off offset:512
	global_load_dwordx4 v[204:207], v[158:159], off offset:576
	v_add_u32_e32 v163, 0xffff8000, v162
	v_lshl_or_b32 v164, v163, 12, v160
	v_add_u32_e32 v165, 0x10000, v164
	v_add_u32_e32 v166, 0x20000, v164
	v_add_u32_e32 v167, 0x30000, v164
	v_add_u32_e32 v168, 0x80000, v164
	v_add_u32_e32 v169, 0x90000, v164
	v_add_u32_e32 v170, 0xa0000, v164
	v_add_u32_e32 v171, 0xb0000, v164
	global_load_dwordx4 v[208:211], v164, s[10:11]
	global_load_dwordx4 v[212:215], v164, s[10:11] offset:64
	global_load_dwordx4 v[216:219], v165, s[10:11]
	global_load_dwordx4 v[220:223], v165, s[10:11] offset:64
	global_load_dwordx4 v[224:227], v166, s[10:11]
	global_load_dwordx4 v[228:231], v166, s[10:11] offset:64
	global_load_dwordx4 v[232:235], v167, s[10:11]
	global_load_dwordx4 v[236:239], v167, s[10:11] offset:64
	global_load_dwordx4 v[240:243], v168, s[10:11]
	global_load_dwordx4 v[244:247], v168, s[10:11] offset:64
	s_cmpk_lt_u32 s4, 0x100
	s_waitcnt vmcnt(9)
	v_pk_fma_f32 v[126:127], v[126:127], v[192:193], v[208:209]
	v_pk_fma_f32 v[128:129], v[128:129], v[194:195], v[210:211]
	global_store_dwordx4 v164, v[126:129], s[16:17]
	global_load_dwordx4 v[208:211], v169, s[10:11]
	s_waitcnt vmcnt(10)
	v_pk_fma_f32 v[98:99], v[98:99], v[196:197], v[212:213]
	v_pk_fma_f32 v[100:101], v[100:101], v[198:199], v[214:215]
	global_store_dwordx4 v164, v[98:101], s[16:17] offset:64
	global_load_dwordx4 v[212:215], v169, s[10:11] offset:64
	s_waitcnt vmcnt(11)
	v_pk_fma_f32 v[122:123], v[122:123], v[192:193], v[216:217]
	v_pk_fma_f32 v[124:125], v[124:125], v[194:195], v[218:219]
	global_store_dwordx4 v165, v[122:125], s[16:17]
	global_load_dwordx4 v[216:219], v170, s[10:11]
	s_waitcnt vmcnt(12)
	v_pk_fma_f32 v[94:95], v[94:95], v[196:197], v[220:221]
	v_pk_fma_f32 v[96:97], v[96:97], v[198:199], v[222:223]
	global_store_dwordx4 v165, v[94:97], s[16:17] offset:64
	global_load_dwordx4 v[220:223], v170, s[10:11] offset:64
	s_waitcnt vmcnt(13)
	v_pk_fma_f32 v[118:119], v[118:119], v[192:193], v[224:225]
	v_pk_fma_f32 v[120:121], v[120:121], v[194:195], v[226:227]
	global_store_dwordx4 v166, v[118:121], s[16:17]
	global_load_dwordx4 v[224:227], v171, s[10:11]
	s_waitcnt vmcnt(14)
;     __device__ __forceinline__ void operator()(Acc& acc, int pm, int pn, int wr, int wc, int fr, int fq) const {
;     ...
; #pragma unroll
;         for (int bj = 0; bj < 2; ++bj)
; #pragma unroll
;             for (int n = 0; n < 2; ++n) {
;                 const f32x4 gv = *reinterpret_cast<const f32x4*>(gp + bj * 128 + n * 16);
; #pragma unroll
;                 for (int ai = 0; ai < 2; ++ai)
; #pragma unroll
;                     for (int m = 0; m < 4; ++m) {
;                         const size_t o = (size_t)(brow + ai * 128 + wr * 64 + m * 16 + fr - rsub) * DM + c0 + bj * 128 + n * 16;
;                         const f32x4 xi = *reinterpret_cast<const f32x4*>(xin + o);
;                         const f32x4 a = acc[ai][bj][m][n];
;                         f32x4 r = {xi[0] + gv[0] * a[0], xi[1] + gv[1] * a[1], xi[2] + gv[2] * a[2], xi[3] + gv[3] * a[3]};
;                         *reinterpret_cast<f32x4*>(xout + o) = r;
;                     }
	v_pk_fma_f32 v[90:91], v[90:91], v[196:197], v[228:229]
	v_pk_fma_f32 v[92:93], v[92:93], v[198:199], v[230:231]
	global_store_dwordx4 v166, v[90:93], s[16:17] offset:64
	global_load_dwordx4 v[228:231], v171, s[10:11] offset:64
	s_waitcnt vmcnt(15)
	v_pk_fma_f32 v[114:115], v[114:115], v[192:193], v[232:233]
	v_pk_fma_f32 v[116:117], v[116:117], v[194:195], v[234:235]
	global_store_dwordx4 v167, v[114:117], s[16:17]
	global_load_dwordx4 v[232:235], v164, s[10:11] offset:512
	s_waitcnt vmcnt(16)
	v_pk_fma_f32 v[82:83], v[82:83], v[196:197], v[236:237]
	v_pk_fma_f32 v[84:85], v[84:85], v[198:199], v[238:239]
	global_store_dwordx4 v167, v[82:85], s[16:17] offset:64
	global_load_dwordx4 v[236:239], v164, s[10:11] offset:576
	s_waitcnt vmcnt(17)
	v_pk_fma_f32 v[110:111], v[110:111], v[192:193], v[240:241]
	v_pk_fma_f32 v[112:113], v[112:113], v[194:195], v[242:243]
	global_store_dwordx4 v168, v[110:113], s[16:17]
	global_load_dwordx4 v[240:243], v165, s[10:11] offset:512
	s_waitcnt vmcnt(18)
	v_pk_fma_f32 v[78:79], v[78:79], v[196:197], v[244:245]
	v_pk_fma_f32 v[80:81], v[80:81], v[198:199], v[246:247]
	global_store_dwordx4 v168, v[78:81], s[16:17] offset:64
	global_load_dwordx4 v[244:247], v165, s[10:11] offset:576
	s_waitcnt vmcnt(18)
	v_pk_fma_f32 v[106:107], v[106:107], v[192:193], v[208:209]
	v_pk_fma_f32 v[108:109], v[108:109], v[194:195], v[210:211]
	global_store_dwordx4 v169, v[106:109], s[16:17]
	global_load_dwordx4 v[208:211], v166, s[10:11] offset:512
	s_waitcnt vmcnt(18)
	v_pk_fma_f32 v[70:71], v[70:71], v[196:197], v[212:213]
	v_pk_fma_f32 v[72:73], v[72:73], v[198:199], v[214:215]
	global_store_dwordx4 v169, v[70:73], s[16:17] offset:64
	global_load_dwordx4 v[212:215], v166, s[10:11] offset:576
	s_waitcnt vmcnt(18)
	v_pk_fma_f32 v[102:103], v[102:103], v[192:193], v[216:217]
	v_pk_fma_f32 v[104:105], v[104:105], v[194:195], v[218:219]
	global_store_dwordx4 v170, v[102:105], s[16:17]
	global_load_dwordx4 v[216:219], v167, s[10:11] offset:512
	s_waitcnt vmcnt(18)
	v_pk_fma_f32 v[62:63], v[62:63], v[196:197], v[220:221]
	v_pk_fma_f32 v[64:65], v[64:65], v[198:199], v[222:223]
	global_store_dwordx4 v170, v[62:65], s[16:17] offset:64
	global_load_dwordx4 v[220:223], v167, s[10:11] offset:576
	s_waitcnt vmcnt(18)
	v_pk_fma_f32 v[86:87], v[86:87], v[192:193], v[224:225]
	v_pk_fma_f32 v[88:89], v[88:89], v[194:195], v[226:227]
	global_store_dwordx4 v171, v[86:89], s[16:17]
	global_load_dwordx4 v[224:227], v168, s[10:11] offset:512
	s_waitcnt vmcnt(18)
	v_pk_fma_f32 v[54:55], v[54:55], v[196:197], v[228:229]
	v_pk_fma_f32 v[56:57], v[56:57], v[198:199], v[230:231]
	global_store_dwordx4 v171, v[54:57], s[16:17] offset:64
	global_load_dwordx4 v[228:231], v168, s[10:11] offset:576
	s_waitcnt vmcnt(18)
	v_pk_fma_f32 v[74:75], v[74:75], v[200:201], v[232:233]
	v_pk_fma_f32 v[76:77], v[76:77], v[202:203], v[234:235]
	global_store_dwordx4 v164, v[74:77], s[16:17] offset:512
	global_load_dwordx4 v[232:235], v169, s[10:11] offset:512
	s_waitcnt vmcnt(18)
	v_pk_fma_f32 v[46:47], v[46:47], v[204:205], v[236:237]
	v_pk_fma_f32 v[48:49], v[48:49], v[206:207], v[238:239]
	global_store_dwordx4 v164, v[46:49], s[16:17] offset:576
	global_load_dwordx4 v[236:239], v169, s[10:11] offset:576
	s_waitcnt vmcnt(18)
	v_pk_fma_f32 v[66:67], v[66:67], v[200:201], v[240:241]
	v_pk_fma_f32 v[68:69], v[68:69], v[202:203], v[242:243]
	global_store_dwordx4 v165, v[66:69], s[16:17] offset:512
	global_load_dwordx4 v[240:243], v170, s[10:11] offset:512
	s_waitcnt vmcnt(18)
	v_pk_fma_f32 v[38:39], v[38:39], v[204:205], v[244:245]
	v_pk_fma_f32 v[40:41], v[40:41], v[206:207], v[246:247]
	global_store_dwordx4 v165, v[38:41], s[16:17] offset:576
	global_load_dwordx4 v[244:247], v170, s[10:11] offset:576
	s_waitcnt vmcnt(18)
	v_pk_fma_f32 v[58:59], v[58:59], v[200:201], v[208:209]
	v_pk_fma_f32 v[60:61], v[60:61], v[202:203], v[210:211]
	global_store_dwordx4 v166, v[58:61], s[16:17] offset:512
	global_load_dwordx4 v[208:211], v171, s[10:11] offset:512
	s_waitcnt vmcnt(18)
	v_pk_fma_f32 v[30:31], v[30:31], v[204:205], v[212:213]
	v_pk_fma_f32 v[32:33], v[32:33], v[206:207], v[214:215]
	global_store_dwordx4 v166, v[30:33], s[16:17] offset:576
	global_load_dwordx4 v[212:215], v171, s[10:11] offset:576
	s_waitcnt vmcnt(18)
	v_pk_fma_f32 v[50:51], v[50:51], v[200:201], v[216:217]
	v_pk_fma_f32 v[52:53], v[52:53], v[202:203], v[218:219]
	global_store_dwordx4 v167, v[50:53], s[16:17] offset:512
	s_waitcnt vmcnt(17)
	v_pk_fma_f32 v[22:23], v[22:23], v[204:205], v[220:221]
	v_pk_fma_f32 v[24:25], v[24:25], v[206:207], v[222:223]
	global_store_dwordx4 v167, v[22:25], s[16:17] offset:576
	s_waitcnt vmcnt(16)
	v_pk_fma_f32 v[42:43], v[42:43], v[200:201], v[224:225]
	v_pk_fma_f32 v[44:45], v[44:45], v[202:203], v[226:227]
	global_store_dwordx4 v168, v[42:45], s[16:17] offset:512
	s_waitcnt vmcnt(15)
	v_pk_fma_f32 v[14:15], v[14:15], v[204:205], v[228:229]
	v_pk_fma_f32 v[16:17], v[16:17], v[206:207], v[230:231]
	global_store_dwordx4 v168, v[14:17], s[16:17] offset:576
	s_waitcnt vmcnt(14)
	v_pk_fma_f32 v[34:35], v[34:35], v[200:201], v[232:233]
	v_pk_fma_f32 v[36:37], v[36:37], v[202:203], v[234:235]
	global_store_dwordx4 v169, v[34:37], s[16:17] offset:512
	s_waitcnt vmcnt(13)
	v_pk_fma_f32 v[10:11], v[10:11], v[204:205], v[236:237]
	v_pk_fma_f32 v[12:13], v[12:13], v[206:207], v[238:239]
	global_store_dwordx4 v169, v[10:13], s[16:17] offset:576
	s_waitcnt vmcnt(12)
	v_pk_fma_f32 v[26:27], v[26:27], v[200:201], v[240:241]
	v_pk_fma_f32 v[28:29], v[28:29], v[202:203], v[242:243]
	global_store_dwordx4 v170, v[26:29], s[16:17] offset:512
	s_waitcnt vmcnt(11)
	v_pk_fma_f32 v[6:7], v[6:7], v[204:205], v[244:245]
	v_pk_fma_f32 v[8:9], v[8:9], v[206:207], v[246:247]
	global_store_dwordx4 v170, v[6:9], s[16:17] offset:576
	s_waitcnt vmcnt(10)
	v_pk_fma_f32 v[18:19], v[18:19], v[200:201], v[208:209]
	v_pk_fma_f32 v[20:21], v[20:21], v[202:203], v[210:211]
	global_store_dwordx4 v171, v[18:21], s[16:17] offset:512
	s_waitcnt vmcnt(9)
	v_pk_fma_f32 v[2:3], v[2:3], v[204:205], v[212:213]
	v_pk_fma_f32 v[4:5], v[4:5], v[206:207], v[214:215]
	global_store_dwordx4 v171, v[2:5], s[16:17] offset:576
	s_mov_b32 s0, 0xf80b0000
	s_mov_b32 s1, -1
	s_waitcnt vmcnt(0)
	s_cbranch_scc0 .LBB0_1411
	s_barrier

; #define PG8_STAGE(bufoff, gbase) do { _Pragma("unroll") for (int _i = 0; _i < 2; ++_i) \
;         __builtin_amdgcn_global_load_lds((const unsigned*)((const char*)(gbase) + voff[_i]), (LAS unsigned*)(lds + (bufoff) + ldsw + _i * 8192), 16, 0, 0); } while (0)
; #define PG8_LDA(dst, b, h) do { _Pragma("unroll") for (int m = 0; m < 4; ++m) _Pragma("unroll") for (int k = 0; k < 2; ++k) dst[m][k] = *(const LAS bf16x8*)(lds + PG8_SA(b, h) + aoff + m * 2048 + k * 1024); } while (0)
; #define PG8_LDB(dst, b, h) do { _Pragma("unroll") for (int n = 0; n < 2; ++n) _Pragma("unroll") for (int k = 0; k < 2; ++k) dst[n][k] = *(const LAS bf16x8*)(lds + PG8_SB(b, h) + boff + n * 2048 + k * 1024); } while (0)
; #define PG8_WAIT_L(n) asm volatile("s_waitcnt lgkmcnt(" #n ")" ::: "memory")
; #define PG8_BAR __builtin_amdgcn_s_barrier()
; #define PG8_SCHED __builtin_amdgcn_sched_barrier(0)
;     ...
;             PG8_LDB(B0, 0, 0); PG8_SCHED; PG8_LDA(At, 0, 0); PG8_STAGE(PG8_SA(1, 1), a1 + hstep);
;             PG8_WAIT_L(8); PG8_BAR; PG8_WAIT_L(0); PG8_MMA(0, 0, At, B0); PG8_BAR; PG8_SCHED;
;             PG8_LDB(B1, 0, 1); PG8_STAGE(PG8_SB(0, 0), b2);
;             PG8_BAR; PG8_WAIT_L(0); PG8_MMA(0, 1, At, B1); PG8_BAR;
;             PG8_LDA(At, 0, 1); PG8_STAGE(PG8_SA(0, 0), a2);
;             PG8_BAR; PG8_WAIT_L(0); PG8_MMA(1, 0, At, B0); PG8_BAR; PG8_SCHED;
.LBB0_1649:
	s_add_u32 s46, s14, 0x100
	s_addc_u32 s47, s15, 0
	s_add_i32 s0, 0, 0x10000
	v_add_u32_e32 v161, s0, v158
	ds_read_b128 v[154:157], v161
	ds_read_b128 v[162:165], v161 offset:1024
	ds_read_b128 v[166:169], v161 offset:2048
	ds_read_b128 v[170:173], v161 offset:3072
	s_cmp_eq_u32 s28, 40
	s_cselect_b32 s53, s11, s47
	s_cselect_b32 s52, s10, s46
	s_cselect_b32 s49, s13, s23
	s_cselect_b32 s48, s12, s22
	v_lshl_add_u64 v[174:175], s[14:15], 0, v[150:151]
	s_add_i32 m0, s56, 0xc000
	ds_read_b128 v[194:197], v160
	ds_read_b128 v[198:201], v160 offset:1024
	ds_read_b128 v[202:205], v160 offset:2048
	ds_read_b128 v[206:209], v160 offset:3072
	ds_read_b128 v[210:213], v160 offset:4096
	ds_read_b128 v[214:217], v160 offset:5120
	ds_read_b128 v[218:221], v160 offset:6144
	ds_read_b128 v[222:225], v160 offset:7168
	global_load_lds_dwordx4 v[174:175], off
	s_add_i32 m0, s56, 0xe000
	v_lshl_add_u64 v[174:175], s[14:15], 0, v[152:153]
	global_load_lds_dwordx4 v[174:175], off
	s_waitcnt lgkmcnt(8)
	s_barrier
	s_waitcnt lgkmcnt(0)
	s_setprio 1
	v_mfma_f32_16x16x32_bf16 v[126:129], v[154:157], v[194:197], v[126:129]
	v_mfma_f32_16x16x32_bf16 v[102:105], v[166:169], v[194:197], v[102:105]
	v_mfma_f32_16x16x32_bf16 v[122:125], v[154:157], v[202:205], v[122:125]
	v_mfma_f32_16x16x32_bf16 v[90:93], v[166:169], v[202:205], v[90:93]
	v_mfma_f32_16x16x32_bf16 v[118:121], v[154:157], v[210:213], v[118:121]
	v_mfma_f32_16x16x32_bf16 v[86:89], v[166:169], v[210:213], v[86:89]
	v_mfma_f32_16x16x32_bf16 v[114:117], v[154:157], v[218:221], v[114:117]
	v_mfma_f32_16x16x32_bf16 v[82:85], v[166:169], v[218:221], v[82:85]
	v_mfma_f32_16x16x32_bf16 v[126:129], v[162:165], v[198:201], v[126:129]
	v_mfma_f32_16x16x32_bf16 v[102:105], v[170:173], v[198:201], v[102:105]
	v_mfma_f32_16x16x32_bf16 v[122:125], v[162:165], v[206:209], v[122:125]
	v_mfma_f32_16x16x32_bf16 v[90:93], v[170:173], v[206:209], v[90:93]
	v_mfma_f32_16x16x32_bf16 v[118:121], v[162:165], v[214:217], v[118:121]
	v_mfma_f32_16x16x32_bf16 v[86:89], v[170:173], v[214:217], v[86:89]
	v_mfma_f32_16x16x32_bf16 v[114:117], v[162:165], v[222:225], v[114:117]
	v_mfma_f32_16x16x32_bf16 v[82:85], v[170:173], v[222:225], v[82:85]
	s_setprio 0
	s_barrier
	s_add_i32 s14, 0, 0x14000
	s_add_i32 s0, s0, s36
	v_add_u32_e32 v161, s14, v158
	v_lshl_add_u64 v[174:175], s[48:49], 0, v[132:133]
	s_mov_b32 m0, s0
	ds_read_b128 v[226:229], v161
	ds_read_b128 v[230:233], v161 offset:1024
	ds_read_b128 v[234:237], v161 offset:2048
	ds_read_b128 v[238:241], v161 offset:3072
	global_load_lds_dwordx4 v[174:175], off
	s_add_i32 m0, s0, 0x2000
	v_lshl_add_u64 v[192:193], s[48:49], 0, v[130:131]
	global_load_lds_dwordx4 v[192:193], off
	s_barrier
	s_waitcnt lgkmcnt(0)
	s_setprio 1
	v_mfma_f32_16x16x32_bf16 v[66:69], v[226:229], v[194:197], v[66:69]
	v_mfma_f32_16x16x32_bf16 v[38:41], v[234:237], v[194:197], v[38:41]
	v_mfma_f32_16x16x32_bf16 v[58:61], v[226:229], v[202:205], v[58:61]
	v_mfma_f32_16x16x32_bf16 v[26:29], v[234:237], v[202:205], v[26:29]
	v_mfma_f32_16x16x32_bf16 v[54:57], v[226:229], v[210:213], v[54:57]
	v_mfma_f32_16x16x32_bf16 v[22:25], v[234:237], v[210:213], v[22:25]
	v_mfma_f32_16x16x32_bf16 v[50:53], v[226:229], v[218:221], v[50:53]
	v_mfma_f32_16x16x32_bf16 v[18:21], v[234:237], v[218:221], v[18:21]
	v_mfma_f32_16x16x32_bf16 v[66:69], v[230:233], v[198:201], v[66:69]
	v_mfma_f32_16x16x32_bf16 v[38:41], v[238:241], v[198:201], v[38:41]
	v_mfma_f32_16x16x32_bf16 v[58:61], v[230:233], v[206:209], v[58:61]
	v_mfma_f32_16x16x32_bf16 v[26:29], v[238:241], v[206:209], v[26:29]
	v_mfma_f32_16x16x32_bf16 v[54:57], v[230:233], v[214:217], v[54:57]
	v_mfma_f32_16x16x32_bf16 v[22:25], v[238:241], v[214:217], v[22:25]
	v_mfma_f32_16x16x32_bf16 v[50:53], v[230:233], v[222:225], v[50:53]
	v_mfma_f32_16x16x32_bf16 v[18:21], v[238:241], v[222:225], v[18:21]
	s_setprio 0
	s_mov_b32 m0, s56
	v_lshl_add_u64 v[242:243], s[52:53], 0, v[132:133]
	s_barrier
	ds_read_b128 v[194:197], v160 offset:16384
	ds_read_b128 v[198:201], v160 offset:17408
	ds_read_b128 v[202:205], v160 offset:18432
	ds_read_b128 v[206:209], v160 offset:19456
	ds_read_b128 v[210:213], v160 offset:20480
	ds_read_b128 v[214:217], v160 offset:21504
	ds_read_b128 v[218:221], v160 offset:22528
	ds_read_b128 v[222:225], v160 offset:23552
	global_load_lds_dwordx4 v[242:243], off
	s_mov_b32 m0, s57
	v_lshl_add_u64 v[244:245], s[52:53], 0, v[130:131]
	global_load_lds_dwordx4 v[244:245], off
	s_barrier
	s_waitcnt lgkmcnt(0)
	s_setprio 1
	v_mfma_f32_16x16x32_bf16 v[110:113], v[154:157], v[194:197], v[110:113]
	v_mfma_f32_16x16x32_bf16 v[78:81], v[166:169], v[194:197], v[78:81]
	v_mfma_f32_16x16x32_bf16 v[106:109], v[154:157], v[202:205], v[106:109]
	v_mfma_f32_16x16x32_bf16 v[74:77], v[166:169], v[202:205], v[74:77]
	v_mfma_f32_16x16x32_bf16 v[98:101], v[154:157], v[210:213], v[98:101]
	v_mfma_f32_16x16x32_bf16 v[70:73], v[166:169], v[210:213], v[70:73]
	v_mfma_f32_16x16x32_bf16 v[94:97], v[154:157], v[218:221], v[94:97]
	v_mfma_f32_16x16x32_bf16 v[62:65], v[166:169], v[218:221], v[62:65]
	v_mfma_f32_16x16x32_bf16 v[110:113], v[162:165], v[198:201], v[110:113]
	v_mfma_f32_16x16x32_bf16 v[78:81], v[170:173], v[198:201], v[78:81]
	v_mfma_f32_16x16x32_bf16 v[106:109], v[162:165], v[206:209], v[106:109]
	v_mfma_f32_16x16x32_bf16 v[74:77], v[170:173], v[206:209], v[74:77]
	v_mfma_f32_16x16x32_bf16 v[98:101], v[162:165], v[214:217], v[98:101]
	v_mfma_f32_16x16x32_bf16 v[70:73], v[170:173], v[214:217], v[70:73]
	v_mfma_f32_16x16x32_bf16 v[94:97], v[162:165], v[222:225], v[94:97]
	v_mfma_f32_16x16x32_bf16 v[62:65], v[170:173], v[222:225], v[62:65]
	s_setprio 0
	s_barrier
; #define PG8_STAGE(bufoff, gbase) do { _Pragma("unroll") for (int _i = 0; _i < 2; ++_i) \
;         __builtin_amdgcn_global_load_lds((const unsigned*)((const char*)(gbase) + voff[_i]), (LAS unsigned*)(lds + (bufoff) + ldsw + _i * 8192), 16, 0, 0); } while (0)
; #define PG8_LDA(dst, b, h) do { _Pragma("unroll") for (int m = 0; m < 4; ++m) _Pragma("unroll") for (int k = 0; k < 2; ++k) dst[m][k] = *(const LAS bf16x8*)(lds + PG8_SA(b, h) + aoff + m * 2048 + k * 1024); } while (0)
; #define PG8_LDB(dst, b, h) do { _Pragma("unroll") for (int n = 0; n < 2; ++n) _Pragma("unroll") for (int k = 0; k < 2; ++k) dst[n][k] = *(const LAS bf16x8*)(lds + PG8_SB(b, h) + boff + n * 2048 + k * 1024); } while (0)
; #define PG8_WAIT_V(n) asm volatile("s_waitcnt vmcnt(" #n ")" ::: "memory")
; #define PG8_WAIT_L(n) asm volatile("s_waitcnt lgkmcnt(" #n ")" ::: "memory")
; #define PG8_BAR __builtin_amdgcn_s_barrier()
; #define PG8_SCHED __builtin_amdgcn_sched_barrier(0)
;     ...
;             PG8_STAGE(PG8_SB(0, 1), b2 + hstep);
;             PG8_WAIT_V(6); PG8_BAR; PG8_MMA(1, 1, At, B1); PG8_BAR;
;             PG8_LDB(B0, 1, 0); PG8_SCHED; PG8_LDA(At, 1, 0); PG8_STAGE(PG8_SA(0, 1), a2 + hstep);
;             PG8_WAIT_L(8); PG8_BAR; PG8_WAIT_L(0); PG8_MMA(0, 0, At, B0); PG8_BAR; PG8_SCHED;
;             PG8_LDB(B1, 1, 1); PG8_STAGE(PG8_SB(1, 0), b3);
;             PG8_BAR; PG8_WAIT_L(0); PG8_MMA(0, 1, At, B1); PG8_BAR;
;             PG8_LDA(At, 1, 1); PG8_STAGE(PG8_SA(1, 0), a3);
;             PG8_BAR; PG8_WAIT_L(0); PG8_MMA(1, 0, At, B0); PG8_BAR; PG8_SCHED;
	s_add_u32 s0, s48, 0xb0000
	s_addc_u32 s1, s49, 0
	s_add_i32 s14, s14, s36
	s_mov_b32 m0, s14
	v_lshl_add_u64 v[154:155], s[0:1], 0, v[132:133]
	global_load_lds_dwordx4 v[154:155], off
	s_add_i32 m0, s14, 0x2000
	v_lshl_add_u64 v[154:155], s[0:1], 0, v[130:131]
	global_load_lds_dwordx4 v[154:155], off
	s_waitcnt vmcnt(6)
	s_barrier
	s_setprio 1
	v_mfma_f32_16x16x32_bf16 v[46:49], v[226:229], v[194:197], v[46:49]
	v_mfma_f32_16x16x32_bf16 v[14:17], v[234:237], v[194:197], v[14:17]
	v_mfma_f32_16x16x32_bf16 v[42:45], v[226:229], v[202:205], v[42:45]
	v_mfma_f32_16x16x32_bf16 v[10:13], v[234:237], v[202:205], v[10:13]
	v_mfma_f32_16x16x32_bf16 v[34:37], v[226:229], v[210:213], v[34:37]
	v_mfma_f32_16x16x32_bf16 v[6:9], v[234:237], v[210:213], v[6:9]
	v_mfma_f32_16x16x32_bf16 v[30:33], v[226:229], v[218:221], v[30:33]
	v_mfma_f32_16x16x32_bf16 v[2:5], v[234:237], v[218:221], v[2:5]
	v_mfma_f32_16x16x32_bf16 v[46:49], v[230:233], v[198:201], v[46:49]
	v_mfma_f32_16x16x32_bf16 v[14:17], v[238:241], v[198:201], v[14:17]
	v_mfma_f32_16x16x32_bf16 v[42:45], v[230:233], v[206:209], v[42:45]
	v_mfma_f32_16x16x32_bf16 v[10:13], v[238:241], v[206:209], v[10:13]
	v_mfma_f32_16x16x32_bf16 v[34:37], v[230:233], v[214:217], v[34:37]
	v_mfma_f32_16x16x32_bf16 v[6:9], v[238:241], v[214:217], v[6:9]
	v_mfma_f32_16x16x32_bf16 v[30:33], v[230:233], v[222:225], v[30:33]
	v_mfma_f32_16x16x32_bf16 v[2:5], v[238:241], v[222:225], v[2:5]
	s_setprio 0
	s_add_i32 s14, 0, 0x18000
	v_add_u32_e32 v161, s14, v158
	s_barrier
	ds_read_b128 v[154:157], v161
	ds_read_b128 v[162:165], v161 offset:1024
	ds_read_b128 v[166:169], v161 offset:2048
	ds_read_b128 v[170:173], v161 offset:3072
	s_add_u32 s0, s52, 0xb0000
	s_addc_u32 s1, s53, 0
	s_mov_b32 m0, s58
	v_lshl_add_u64 v[226:227], s[0:1], 0, v[132:133]
	ds_read_b128 v[194:197], v160 offset:32768
	ds_read_b128 v[198:201], v160 offset:33792
	ds_read_b128 v[202:205], v160 offset:34816
	ds_read_b128 v[206:209], v160 offset:35840
	ds_read_b128 v[210:213], v160 offset:36864
	ds_read_b128 v[214:217], v160 offset:37888
	ds_read_b128 v[218:221], v160 offset:38912
	ds_read_b128 v[222:225], v160 offset:39936
	global_load_lds_dwordx4 v[226:227], off
	s_mov_b32 m0, s59
	v_lshl_add_u64 v[226:227], s[0:1], 0, v[130:131]
	global_load_lds_dwordx4 v[226:227], off
	s_waitcnt lgkmcnt(8)
	s_barrier
	s_waitcnt lgkmcnt(0)
	s_setprio 1
	v_mfma_f32_16x16x32_bf16 v[126:129], v[154:157], v[194:197], v[126:129]
	v_mfma_f32_16x16x32_bf16 v[102:105], v[166:169], v[194:197], v[102:105]
	v_mfma_f32_16x16x32_bf16 v[122:125], v[154:157], v[202:205], v[122:125]
	v_mfma_f32_16x16x32_bf16 v[90:93], v[166:169], v[202:205], v[90:93]
	v_mfma_f32_16x16x32_bf16 v[118:121], v[154:157], v[210:213], v[118:121]
	v_mfma_f32_16x16x32_bf16 v[86:89], v[166:169], v[210:213], v[86:89]
	v_mfma_f32_16x16x32_bf16 v[114:117], v[154:157], v[218:221], v[114:117]
	v_mfma_f32_16x16x32_bf16 v[82:85], v[166:169], v[218:221], v[82:85]
	v_mfma_f32_16x16x32_bf16 v[126:129], v[162:165], v[198:201], v[126:129]
	v_mfma_f32_16x16x32_bf16 v[102:105], v[170:173], v[198:201], v[102:105]
	v_mfma_f32_16x16x32_bf16 v[122:125], v[162:165], v[206:209], v[122:125]
	v_mfma_f32_16x16x32_bf16 v[90:93], v[170:173], v[206:209], v[90:93]
	v_mfma_f32_16x16x32_bf16 v[118:121], v[162:165], v[214:217], v[118:121]
	v_mfma_f32_16x16x32_bf16 v[86:89], v[170:173], v[214:217], v[86:89]
	v_mfma_f32_16x16x32_bf16 v[114:117], v[162:165], v[222:225], v[114:117]
	v_mfma_f32_16x16x32_bf16 v[82:85], v[170:173], v[222:225], v[82:85]
	s_setprio 0
	s_barrier
	s_add_i32 s15, 0, 0x1c000
	s_add_i32 s0, s14, s36
	v_add_u32_e32 v161, s15, v158
	v_lshl_add_u64 v[174:175], v[174:175], 0, s[88:89]
	s_mov_b32 m0, s0
	ds_read_b128 v[226:229], v161
	ds_read_b128 v[230:233], v161 offset:1024
	ds_read_b128 v[234:237], v161 offset:2048
	ds_read_b128 v[238:241], v161 offset:3072
	global_load_lds_dwordx4 v[174:175], off
	s_add_i32 m0, s0, 0x2000
	v_lshl_add_u64 v[174:175], v[192:193], 0, s[88:89]
	global_load_lds_dwordx4 v[174:175], off
	s_barrier
	s_waitcnt lgkmcnt(0)
	s_setprio 1
	v_mfma_f32_16x16x32_bf16 v[66:69], v[226:229], v[194:197], v[66:69]
	v_mfma_f32_16x16x32_bf16 v[38:41], v[234:237], v[194:197], v[38:41]
	v_mfma_f32_16x16x32_bf16 v[58:61], v[226:229], v[202:205], v[58:61]
	v_mfma_f32_16x16x32_bf16 v[26:29], v[234:237], v[202:205], v[26:29]
	v_mfma_f32_16x16x32_bf16 v[54:57], v[226:229], v[210:213], v[54:57]
	v_mfma_f32_16x16x32_bf16 v[22:25], v[234:237], v[210:213], v[22:25]
	v_mfma_f32_16x16x32_bf16 v[50:53], v[226:229], v[218:221], v[50:53]
	v_mfma_f32_16x16x32_bf16 v[18:21], v[234:237], v[218:221], v[18:21]
	v_mfma_f32_16x16x32_bf16 v[66:69], v[230:233], v[198:201], v[66:69]
	v_mfma_f32_16x16x32_bf16 v[38:41], v[238:241], v[198:201], v[38:41]
	v_mfma_f32_16x16x32_bf16 v[58:61], v[230:233], v[206:209], v[58:61]
	v_mfma_f32_16x16x32_bf16 v[26:29], v[238:241], v[206:209], v[26:29]
	v_mfma_f32_16x16x32_bf16 v[54:57], v[230:233], v[214:217], v[54:57]
	v_mfma_f32_16x16x32_bf16 v[22:25], v[238:241], v[214:217], v[22:25]
	v_mfma_f32_16x16x32_bf16 v[50:53], v[230:233], v[222:225], v[50:53]
	v_mfma_f32_16x16x32_bf16 v[18:21], v[238:241], v[222:225], v[18:21]
	s_setprio 0
	s_mov_b32 m0, s60
	v_lshl_add_u64 v[174:175], v[242:243], 0, s[88:89]
	s_barrier
	ds_read_b128 v[194:197], v160 offset:49152
	ds_read_b128 v[198:201], v160 offset:50176
	ds_read_b128 v[202:205], v160 offset:51200
	ds_read_b128 v[206:209], v160 offset:52224
	ds_read_b128 v[210:213], v160 offset:53248
	ds_read_b128 v[214:217], v160 offset:54272
	ds_read_b128 v[218:221], v160 offset:55296
	ds_read_b128 v[222:225], v160 offset:56320
	global_load_lds_dwordx4 v[174:175], off
	s_mov_b32 m0, s61
	v_lshl_add_u64 v[174:175], v[244:245], 0, s[88:89]
	global_load_lds_dwordx4 v[174:175], off
	s_barrier
; #define PG8_STAGE(bufoff, gbase) do { _Pragma("unroll") for (int _i = 0; _i < 2; ++_i) \
;         __builtin_amdgcn_global_load_lds((const unsigned*)((const char*)(gbase) + voff[_i]), (LAS unsigned*)(lds + (bufoff) + ldsw + _i * 8192), 16, 0, 0); } while (0)
; #define PG8_WAIT_V(n) asm volatile("s_waitcnt vmcnt(" #n ")" ::: "memory")
; #define PG8_WAIT_L(n) asm volatile("s_waitcnt lgkmcnt(" #n ")" ::: "memory")
; #define PG8_BAR __builtin_amdgcn_s_barrier()
; #define PG8_SCHED __builtin_amdgcn_sched_barrier(0)
;     ...
;             PG8_BAR; PG8_WAIT_L(0); PG8_MMA(1, 0, At, B0); PG8_BAR; PG8_SCHED;
;             PG8_STAGE(PG8_SB(1, 1), b3 + hstep);
;             PG8_WAIT_V(6); PG8_BAR; PG8_MMA(1, 1, At, B1); PG8_BAR;
;         }
;         E(acc, cur.pm + pm0, cur.pn, wr, wc, fr, fq);
;     __device__ __forceinline__ void operator()(Acc& acc, int pm, int pn, int wr, int wc, int fr, int fq) const {
;         const int brow = pm * 256;
;         const bool lat = brow < T_LAT;
;         const float* xin = lat ? xin_lat : xin_ctx;
;         float* xout = lat ? xout_lat : xout_ctx;
;         const int rsub = lat ? 0 : T_LAT;
;         const int mi = lat ? (brow >> 12) : 8;
;         const int c0 = pn * 256 + wc * 32 + fq * 4;
;         const float* gp = modv_l + (size_t)mi * 6144 + gate_i * 1024 + c0;
; #pragma unroll
;         for (int bj = 0; bj < 2; ++bj)
; #pragma unroll
;             for (int n = 0; n < 2; ++n) {
;                 const f32x4 gv = *reinterpret_cast<const f32x4*>(gp + bj * 128 + n * 16);
; #pragma unroll
;                 for (int ai = 0; ai < 2; ++ai)
; #pragma unroll
;                     for (int m = 0; m < 4; ++m) {
;                         const size_t o = (size_t)(brow + ai * 128 + wr * 64 + m * 16 + fr - rsub) * DM + c0 + bj * 128 + n * 16;
;                         const f32x4 xi = *reinterpret_cast<const f32x4*>(xin + o);
;                         const f32x4 a = acc[ai][bj][m][n];
;                         f32x4 r = {xi[0] + gv[0] * a[0], xi[1] + gv[1] * a[1], xi[2] + gv[2] * a[2], xi[3] + gv[3] * a[3]};
;                         *reinterpret_cast<f32x4*>(xout + o) = r;
	s_waitcnt lgkmcnt(0)
	s_setprio 1
	v_mfma_f32_16x16x32_bf16 v[110:113], v[154:157], v[194:197], v[110:113]
	v_mfma_f32_16x16x32_bf16 v[78:81], v[166:169], v[194:197], v[78:81]
	v_mfma_f32_16x16x32_bf16 v[106:109], v[154:157], v[202:205], v[106:109]
	v_mfma_f32_16x16x32_bf16 v[74:77], v[166:169], v[202:205], v[74:77]
	v_mfma_f32_16x16x32_bf16 v[98:101], v[154:157], v[210:213], v[98:101]
	v_mfma_f32_16x16x32_bf16 v[70:73], v[166:169], v[210:213], v[70:73]
	v_mfma_f32_16x16x32_bf16 v[94:97], v[154:157], v[218:221], v[94:97]
	v_mfma_f32_16x16x32_bf16 v[62:65], v[166:169], v[218:221], v[62:65]
	v_mfma_f32_16x16x32_bf16 v[110:113], v[162:165], v[198:201], v[110:113]
	v_mfma_f32_16x16x32_bf16 v[78:81], v[170:173], v[198:201], v[78:81]
	v_mfma_f32_16x16x32_bf16 v[106:109], v[162:165], v[206:209], v[106:109]
	v_mfma_f32_16x16x32_bf16 v[74:77], v[170:173], v[206:209], v[74:77]
	v_mfma_f32_16x16x32_bf16 v[98:101], v[162:165], v[214:217], v[98:101]
	v_mfma_f32_16x16x32_bf16 v[70:73], v[170:173], v[214:217], v[70:73]
	v_mfma_f32_16x16x32_bf16 v[94:97], v[162:165], v[222:225], v[94:97]
	v_mfma_f32_16x16x32_bf16 v[62:65], v[170:173], v[222:225], v[62:65]
	s_setprio 0
	s_barrier
	s_add_u32 s0, s48, 0xb0080
	s_addc_u32 s1, s49, 0
	s_add_i32 s14, s15, s36
	s_mov_b32 m0, s14
	v_lshl_add_u64 v[154:155], s[0:1], 0, v[132:133]
	global_load_lds_dwordx4 v[154:155], off
	s_add_i32 m0, s14, 0x2000
	v_lshl_add_u64 v[154:155], s[0:1], 0, v[130:131]
	global_load_lds_dwordx4 v[154:155], off
	s_waitcnt vmcnt(6)
	s_barrier
	s_setprio 1
	v_mfma_f32_16x16x32_bf16 v[46:49], v[226:229], v[194:197], v[46:49]
	v_mfma_f32_16x16x32_bf16 v[14:17], v[234:237], v[194:197], v[14:17]
	v_mfma_f32_16x16x32_bf16 v[42:45], v[226:229], v[202:205], v[42:45]
	v_mfma_f32_16x16x32_bf16 v[10:13], v[234:237], v[202:205], v[10:13]
	v_mfma_f32_16x16x32_bf16 v[34:37], v[226:229], v[210:213], v[34:37]
	v_mfma_f32_16x16x32_bf16 v[6:9], v[234:237], v[210:213], v[6:9]
	v_mfma_f32_16x16x32_bf16 v[30:33], v[226:229], v[218:221], v[30:33]
	v_mfma_f32_16x16x32_bf16 v[2:5], v[234:237], v[218:221], v[2:5]
	v_mfma_f32_16x16x32_bf16 v[46:49], v[230:233], v[198:201], v[46:49]
	v_mfma_f32_16x16x32_bf16 v[14:17], v[238:241], v[198:201], v[14:17]
	v_mfma_f32_16x16x32_bf16 v[42:45], v[230:233], v[206:209], v[42:45]
	v_mfma_f32_16x16x32_bf16 v[10:13], v[238:241], v[206:209], v[10:13]
	v_mfma_f32_16x16x32_bf16 v[34:37], v[230:233], v[214:217], v[34:37]
	v_mfma_f32_16x16x32_bf16 v[6:9], v[238:241], v[214:217], v[6:9]
	v_mfma_f32_16x16x32_bf16 v[30:33], v[230:233], v[222:225], v[30:33]
	v_mfma_f32_16x16x32_bf16 v[2:5], v[238:241], v[222:225], v[2:5]
	s_setprio 0
	s_add_i32 s28, s28, 2
	s_add_u32 s22, s22, 0x100
	s_addc_u32 s23, s23, 0
	s_cmp_gt_u32 s28, 41
	s_mov_b64 s[14:15], s[46:47]
	s_barrier
	s_cbranch_scc0 .LBB0_1649
	s_lshl_b32 s22, s4, 8
	v_readlane_b32 s64, v254, 6
	s_cmpk_lt_i32 s4, 0x80
	v_readlane_b32 s66, v254, 8
	v_readlane_b32 s67, v254, 9
	v_readlane_b32 s68, v254, 10
	v_readlane_b32 s69, v254, 11
	s_cselect_b32 s15, s67, s69
	s_cselect_b32 s14, s66, s68
	s_cselect_b32 s23, 0, 0xffff8000
	s_min_i32 s0, s4, 0x80
	s_ashr_i32 s0, s0, 4
	s_mul_hi_i32 s1, s0, 0x6000
	s_mulk_i32 s0, 0x6000
	s_add_u32 s0, s50, s0
	s_addc_u32 s1, s51, s1
	s_add_i32 s23, s23, s22
	s_add_u32 s0, s0, 0x5000
	s_addc_u32 s1, s1, 0
	v_lshl_or_b32 v154, s7, 8, v159
	v_add_u32_e32 v172, s23, v1
	v_ashrrev_i32_e32 v155, 31, v154
	v_lshl_add_u64 v[156:157], v[154:155], 2, s[0:1]
	global_load_dwordx4 v[162:165], v[156:157], off
	global_load_dwordx4 v[166:169], v[156:157], off offset:64
	global_load_dwordx4 v[192:195], v[156:157], off offset:512
	global_load_dwordx4 v[196:199], v[156:157], off offset:576
	v_lshl_add_u32 v161, v172, 10, v154
	v_lshlrev_b32_e32 v161, 2, v161
	v_add_u32_e32 v170, 0x10000, v161
	v_add_u32_e32 v171, 0x20000, v161
	v_add_u32_e32 v154, 0x30000, v161
	v_add_u32_e32 v155, 0x80000, v161
	v_add_u32_e32 v172, 0x90000, v161
	v_add_u32_e32 v156, 0xa0000, v161
	v_add_u32_e32 v157, 0xb0000, v161
	global_load_dwordx4 v[200:203], v161, s[14:15]
	global_load_dwordx4 v[204:207], v161, s[14:15] offset:64
	global_load_dwordx4 v[208:211], v170, s[14:15]
	global_load_dwordx4 v[212:215], v170, s[14:15] offset:64
	global_load_dwordx4 v[216:219], v171, s[14:15]
	global_load_dwordx4 v[220:223], v171, s[14:15] offset:64
	global_load_dwordx4 v[224:227], v154, s[14:15]
	global_load_dwordx4 v[228:231], v154, s[14:15] offset:64
	global_load_dwordx4 v[232:235], v155, s[14:15]
	global_load_dwordx4 v[236:239], v155, s[14:15] offset:64
	global_load_dwordx4 v[240:243], v172, s[14:15]
	s_and_b64 vcc, exec, s[44:45]
	s_mov_b32 s7, s18
	s_mov_b32 s4, s19
	s_mov_b64 s[52:53], s[12:13]
	v_readlane_b32 s65, v254, 7
	v_readlane_b32 s70, v254, 12
	v_readlane_b32 s71, v254, 13
	s_waitcnt vmcnt(10)
	v_pk_fma_f32 v[126:127], v[126:127], v[162:163], v[200:201]
	v_pk_fma_f32 v[128:129], v[128:129], v[164:165], v[202:203]
	global_store_dwordx4 v161, v[126:129], s[14:15]
	global_load_dwordx4 v[200:203], v172, s[14:15] offset:64
	s_waitcnt vmcnt(11)
	v_pk_fma_f32 v[102:103], v[102:103], v[166:167], v[204:205]
	v_pk_fma_f32 v[104:105], v[104:105], v[168:169], v[206:207]
	global_store_dwordx4 v161, v[102:105], s[14:15] offset:64
	global_load_dwordx4 v[204:207], v156, s[14:15]
	s_waitcnt vmcnt(12)
	v_pk_fma_f32 v[122:123], v[122:123], v[162:163], v[208:209]
	v_pk_fma_f32 v[124:125], v[124:125], v[164:165], v[210:211]
	global_store_dwordx4 v170, v[122:125], s[14:15]
	global_load_dwordx4 v[208:211], v156, s[14:15] offset:64
	s_waitcnt vmcnt(13)
;     __device__ __forceinline__ void operator()(Acc& acc, int pm, int pn, int wr, int wc, int fr, int fq) const {
;     ...
; #pragma unroll
;         for (int bj = 0; bj < 2; ++bj)
; #pragma unroll
;             for (int n = 0; n < 2; ++n) {
;                 const f32x4 gv = *reinterpret_cast<const f32x4*>(gp + bj * 128 + n * 16);
; #pragma unroll
;                 for (int ai = 0; ai < 2; ++ai)
; #pragma unroll
;                     for (int m = 0; m < 4; ++m) {
;                         const size_t o = (size_t)(brow + ai * 128 + wr * 64 + m * 16 + fr - rsub) * DM + c0 + bj * 128 + n * 16;
;                         const f32x4 xi = *reinterpret_cast<const f32x4*>(xin + o);
;                         const f32x4 a = acc[ai][bj][m][n];
;                         f32x4 r = {xi[0] + gv[0] * a[0], xi[1] + gv[1] * a[1], xi[2] + gv[2] * a[2], xi[3] + gv[3] * a[3]};
;                         *reinterpret_cast<f32x4*>(xout + o) = r;
;                     }
	v_pk_fma_f32 v[90:91], v[90:91], v[166:167], v[212:213]
	v_pk_fma_f32 v[92:93], v[92:93], v[168:169], v[214:215]
	global_store_dwordx4 v170, v[90:93], s[14:15] offset:64
	global_load_dwordx4 v[212:215], v157, s[14:15]
	s_waitcnt vmcnt(14)
	v_pk_fma_f32 v[118:119], v[118:119], v[162:163], v[216:217]
	v_pk_fma_f32 v[120:121], v[120:121], v[164:165], v[218:219]
	global_store_dwordx4 v171, v[118:121], s[14:15]
	global_load_dwordx4 v[216:219], v157, s[14:15] offset:64
	s_waitcnt vmcnt(15)
	v_pk_fma_f32 v[86:87], v[86:87], v[166:167], v[220:221]
	v_pk_fma_f32 v[88:89], v[88:89], v[168:169], v[222:223]
	global_store_dwordx4 v171, v[86:89], s[14:15] offset:64
	global_load_dwordx4 v[220:223], v161, s[14:15] offset:512
	s_waitcnt vmcnt(16)
	v_pk_fma_f32 v[114:115], v[114:115], v[162:163], v[224:225]
	v_pk_fma_f32 v[116:117], v[116:117], v[164:165], v[226:227]
	global_store_dwordx4 v154, v[114:117], s[14:15]
	global_load_dwordx4 v[224:227], v161, s[14:15] offset:576
	s_waitcnt vmcnt(17)
	v_pk_fma_f32 v[82:83], v[82:83], v[166:167], v[228:229]
	v_pk_fma_f32 v[84:85], v[84:85], v[168:169], v[230:231]
	global_store_dwordx4 v154, v[82:85], s[14:15] offset:64
	global_load_dwordx4 v[228:231], v170, s[14:15] offset:512
	s_waitcnt vmcnt(18)
	v_pk_fma_f32 v[110:111], v[110:111], v[162:163], v[232:233]
	v_pk_fma_f32 v[112:113], v[112:113], v[164:165], v[234:235]
	global_store_dwordx4 v155, v[110:113], s[14:15]
	global_load_dwordx4 v[232:235], v170, s[14:15] offset:576
	s_waitcnt vmcnt(19)
	v_pk_fma_f32 v[78:79], v[78:79], v[166:167], v[236:237]
	v_pk_fma_f32 v[80:81], v[80:81], v[168:169], v[238:239]
	global_store_dwordx4 v155, v[78:81], s[14:15] offset:64
	global_load_dwordx4 v[236:239], v171, s[14:15] offset:512
	s_waitcnt vmcnt(20)
	v_pk_fma_f32 v[106:107], v[106:107], v[162:163], v[240:241]
	v_pk_fma_f32 v[108:109], v[108:109], v[164:165], v[242:243]
	global_store_dwordx4 v172, v[106:109], s[14:15]
	global_load_dwordx4 v[240:243], v171, s[14:15] offset:576
	s_waitcnt vmcnt(20)
	v_pk_fma_f32 v[74:75], v[74:75], v[166:167], v[200:201]
	v_pk_fma_f32 v[76:77], v[76:77], v[168:169], v[202:203]
	global_store_dwordx4 v172, v[74:77], s[14:15] offset:64
	global_load_dwordx4 v[200:203], v154, s[14:15] offset:512
	s_waitcnt vmcnt(20)
	v_pk_fma_f32 v[98:99], v[98:99], v[162:163], v[204:205]
	v_pk_fma_f32 v[100:101], v[100:101], v[164:165], v[206:207]
	global_store_dwordx4 v156, v[98:101], s[14:15]
	global_load_dwordx4 v[204:207], v154, s[14:15] offset:576
	s_waitcnt vmcnt(20)
	v_pk_fma_f32 v[70:71], v[70:71], v[166:167], v[208:209]
	v_pk_fma_f32 v[72:73], v[72:73], v[168:169], v[210:211]
	global_store_dwordx4 v156, v[70:73], s[14:15] offset:64
	global_load_dwordx4 v[208:211], v155, s[14:15] offset:512
	s_waitcnt vmcnt(20)
	v_pk_fma_f32 v[94:95], v[94:95], v[162:163], v[212:213]
	v_pk_fma_f32 v[96:97], v[96:97], v[164:165], v[214:215]
	global_store_dwordx4 v157, v[94:97], s[14:15]
	global_load_dwordx4 v[212:215], v155, s[14:15] offset:576
	s_waitcnt vmcnt(20)
	v_pk_fma_f32 v[62:63], v[62:63], v[166:167], v[216:217]
	v_pk_fma_f32 v[64:65], v[64:65], v[168:169], v[218:219]
	global_store_dwordx4 v157, v[62:65], s[14:15] offset:64
	global_load_dwordx4 v[216:219], v172, s[14:15] offset:512
	s_waitcnt vmcnt(20)
	v_pk_fma_f32 v[66:67], v[66:67], v[192:193], v[220:221]
	v_pk_fma_f32 v[68:69], v[68:69], v[194:195], v[222:223]
	global_store_dwordx4 v161, v[66:69], s[14:15] offset:512
	global_load_dwordx4 v[220:223], v172, s[14:15] offset:576
	s_waitcnt vmcnt(20)
	v_pk_fma_f32 v[38:39], v[38:39], v[196:197], v[224:225]
	v_pk_fma_f32 v[40:41], v[40:41], v[198:199], v[226:227]
	global_store_dwordx4 v161, v[38:41], s[14:15] offset:576
	global_load_dwordx4 v[224:227], v156, s[14:15] offset:512
	s_waitcnt vmcnt(20)
	v_pk_fma_f32 v[58:59], v[58:59], v[192:193], v[228:229]
	v_pk_fma_f32 v[60:61], v[60:61], v[194:195], v[230:231]
	global_store_dwordx4 v170, v[58:61], s[14:15] offset:512
	global_load_dwordx4 v[228:231], v156, s[14:15] offset:576
	s_waitcnt vmcnt(20)
	v_pk_fma_f32 v[26:27], v[26:27], v[196:197], v[232:233]
	v_pk_fma_f32 v[28:29], v[28:29], v[198:199], v[234:235]
	global_store_dwordx4 v170, v[26:29], s[14:15] offset:576
	global_load_dwordx4 v[232:235], v157, s[14:15] offset:512
	s_waitcnt vmcnt(20)
	v_pk_fma_f32 v[54:55], v[54:55], v[192:193], v[236:237]
	v_pk_fma_f32 v[56:57], v[56:57], v[194:195], v[238:239]
	global_store_dwordx4 v171, v[54:57], s[14:15] offset:512
	global_load_dwordx4 v[236:239], v157, s[14:15] offset:576
	s_waitcnt vmcnt(20)
	v_pk_fma_f32 v[22:23], v[22:23], v[196:197], v[240:241]
	v_pk_fma_f32 v[24:25], v[24:25], v[198:199], v[242:243]
	global_store_dwordx4 v171, v[22:25], s[14:15] offset:576
	s_waitcnt vmcnt(19)
	v_pk_fma_f32 v[50:51], v[50:51], v[192:193], v[200:201]
	v_pk_fma_f32 v[52:53], v[52:53], v[194:195], v[202:203]
	global_store_dwordx4 v154, v[50:53], s[14:15] offset:512
	s_waitcnt vmcnt(18)
	v_pk_fma_f32 v[18:19], v[18:19], v[196:197], v[204:205]
	v_pk_fma_f32 v[20:21], v[20:21], v[198:199], v[206:207]
	global_store_dwordx4 v154, v[18:21], s[14:15] offset:576
	s_waitcnt vmcnt(17)
	v_pk_fma_f32 v[46:47], v[46:47], v[192:193], v[208:209]
	v_pk_fma_f32 v[48:49], v[48:49], v[194:195], v[210:211]
	global_store_dwordx4 v155, v[46:49], s[14:15] offset:512
	s_waitcnt vmcnt(16)
	v_pk_fma_f32 v[14:15], v[14:15], v[196:197], v[212:213]
	v_pk_fma_f32 v[16:17], v[16:17], v[198:199], v[214:215]
	global_store_dwordx4 v155, v[14:17], s[14:15] offset:576
	s_waitcnt vmcnt(15)
	v_pk_fma_f32 v[42:43], v[42:43], v[192:193], v[216:217]
	v_pk_fma_f32 v[44:45], v[44:45], v[194:195], v[218:219]
	global_store_dwordx4 v172, v[42:45], s[14:15] offset:512
	s_waitcnt vmcnt(14)
	v_pk_fma_f32 v[10:11], v[10:11], v[196:197], v[220:221]
	v_pk_fma_f32 v[12:13], v[12:13], v[198:199], v[222:223]
	global_store_dwordx4 v172, v[10:13], s[14:15] offset:576
	s_waitcnt vmcnt(13)
	v_pk_fma_f32 v[34:35], v[34:35], v[192:193], v[224:225]
	v_pk_fma_f32 v[36:37], v[36:37], v[194:195], v[226:227]
	global_store_dwordx4 v156, v[34:37], s[14:15] offset:512
	s_waitcnt vmcnt(12)
	v_pk_fma_f32 v[6:7], v[6:7], v[196:197], v[228:229]
	v_pk_fma_f32 v[8:9], v[8:9], v[198:199], v[230:231]
	global_store_dwordx4 v156, v[6:9], s[14:15] offset:576
	s_waitcnt vmcnt(11)
	v_pk_fma_f32 v[30:31], v[30:31], v[192:193], v[232:233]
	v_pk_fma_f32 v[32:33], v[32:33], v[194:195], v[234:235]
	global_store_dwordx4 v157, v[30:33], s[14:15] offset:512
	s_waitcnt vmcnt(10)
	v_pk_fma_f32 v[2:3], v[2:3], v[196:197], v[236:237]
	v_pk_fma_f32 v[4:5], v[4:5], v[198:199], v[238:239]
	global_store_dwordx4 v157, v[2:5], s[14:15] offset:576
	s_mov_b64 s[14:15], s[10:11]
	s_mov_b64 s[0:1], 0x5000
	s_cbranch_vccz .LBB0_1642
	s_waitcnt vmcnt(0)
	s_cmpk_gt_u32 s16, 0xff
	s_cbranch_scc1 .LBB0_1653
	s_barrier

; #define PG8_STAGE(bufoff, gbase) do { _Pragma("unroll") for (int _i = 0; _i < 2; ++_i) \
;         __builtin_amdgcn_global_load_lds((const unsigned*)((const char*)(gbase) + voff[_i]), (LAS unsigned*)(lds + (bufoff) + ldsw + _i * 8192), 16, 0, 0); } while (0)
; #define PG8_LDA(dst, b, h) do { _Pragma("unroll") for (int m = 0; m < 4; ++m) _Pragma("unroll") for (int k = 0; k < 2; ++k) dst[m][k] = *(const LAS bf16x8*)(lds + PG8_SA(b, h) + aoff + m * 2048 + k * 1024); } while (0)
; #define PG8_LDB(dst, b, h) do { _Pragma("unroll") for (int n = 0; n < 2; ++n) _Pragma("unroll") for (int k = 0; k < 2; ++k) dst[n][k] = *(const LAS bf16x8*)(lds + PG8_SB(b, h) + boff + n * 2048 + k * 1024); } while (0)
; #define PG8_WAIT_L(n) asm volatile("s_waitcnt lgkmcnt(" #n ")" ::: "memory")
; #define PG8_BAR __builtin_amdgcn_s_barrier()
; #define PG8_SCHED __builtin_amdgcn_sched_barrier(0)
;     ...
;         const bool has_next = S.next(ui + 1, nxt);
;         const char* nA = has_next ? (const char*)gA + (size_t)nxt.pm * tstep : cA; const char* nB = has_next ? (const char*)gBt + (size_t)nxt.pn * tstep : cB;
;         for (int t = 0; t < nt; t += 2) {
;             const bool last = (t == nt - 2);
;             const char* a1 = cA + (size_t)(t + 1) * kstep;
;             const char* a2 = last ? nA : cA + (size_t)(t + 2) * kstep; const char* b2 = last ? nB : cB + (size_t)(t + 2) * kstep;
;             const char* a3 = a2 + kstep; const char* b3 = b2 + kstep;
;             PG8_LDB(B0, 0, 0); PG8_SCHED; PG8_LDA(At, 0, 0); PG8_STAGE(PG8_SA(1, 1), a1 + hstep);
;             PG8_WAIT_L(8); PG8_BAR; PG8_WAIT_L(0); PG8_MMA(0, 0, At, B0); PG8_BAR; PG8_SCHED;
;             PG8_LDB(B1, 0, 1); PG8_STAGE(PG8_SB(0, 0), b2);
;             PG8_BAR; PG8_WAIT_L(0); PG8_MMA(0, 1, At, B1); PG8_BAR;
;             PG8_LDA(At, 0, 1); PG8_STAGE(PG8_SA(0, 0), a2);
;             PG8_BAR; PG8_WAIT_L(0); PG8_MMA(1, 0, At, B0); PG8_BAR; PG8_SCHED;
.LBB0_1832:
	s_add_u32 s0, s12, 0xf4f50080
	s_addc_u32 s1, s13, -1
	s_cmp_lg_u32 s28, 40
	s_cselect_b32 s0, s0, 0
	s_cselect_b32 s1, s1, 0
	s_add_u32 s40, s44, s0
	s_addc_u32 s41, s45, s1
	s_add_i32 s29, 0, 0x10000
	v_add_u32_e32 v157, s29, v155
	ds_read_b128 v[158:161], v157
	ds_read_b128 v[162:165], v157 offset:1024
	ds_read_b128 v[166:169], v157 offset:2048
	ds_read_b128 v[170:173], v157 offset:3072
	s_add_u32 s14, s10, s0
	s_addc_u32 s15, s11, s1
	v_lshl_add_u64 v[174:175], v[150:151], 0, s[12:13]
	s_add_i32 m0, s7, 0xc000
	ds_read_b128 v[194:197], v156
	ds_read_b128 v[198:201], v156 offset:1024
	ds_read_b128 v[202:205], v156 offset:2048
	ds_read_b128 v[206:209], v156 offset:3072
	ds_read_b128 v[210:213], v156 offset:4096
	ds_read_b128 v[214:217], v156 offset:5120
	ds_read_b128 v[218:221], v156 offset:6144
	ds_read_b128 v[222:225], v156 offset:7168
	global_load_lds_dwordx4 v[174:175], off
	s_add_i32 m0, s7, 0xe000
	v_lshl_add_u64 v[174:175], v[152:153], 0, s[12:13]
	global_load_lds_dwordx4 v[174:175], off
	s_waitcnt lgkmcnt(8)
	s_barrier
	s_waitcnt lgkmcnt(0)
	s_setprio 1
	v_mfma_f32_16x16x32_bf16 v[126:129], v[158:161], v[194:197], v[126:129]
	v_mfma_f32_16x16x32_bf16 v[102:105], v[166:169], v[194:197], v[102:105]
	v_mfma_f32_16x16x32_bf16 v[122:125], v[158:161], v[202:205], v[122:125]
	v_mfma_f32_16x16x32_bf16 v[90:93], v[166:169], v[202:205], v[90:93]
	v_mfma_f32_16x16x32_bf16 v[118:121], v[158:161], v[210:213], v[118:121]
	v_mfma_f32_16x16x32_bf16 v[86:89], v[166:169], v[210:213], v[86:89]
	v_mfma_f32_16x16x32_bf16 v[114:117], v[158:161], v[218:221], v[114:117]
	v_mfma_f32_16x16x32_bf16 v[82:85], v[166:169], v[218:221], v[82:85]
	v_mfma_f32_16x16x32_bf16 v[126:129], v[162:165], v[198:201], v[126:129]
	v_mfma_f32_16x16x32_bf16 v[102:105], v[170:173], v[198:201], v[102:105]
	v_mfma_f32_16x16x32_bf16 v[122:125], v[162:165], v[206:209], v[122:125]
	v_mfma_f32_16x16x32_bf16 v[90:93], v[170:173], v[206:209], v[90:93]
	v_mfma_f32_16x16x32_bf16 v[118:121], v[162:165], v[214:217], v[118:121]
	v_mfma_f32_16x16x32_bf16 v[86:89], v[170:173], v[214:217], v[86:89]
	v_mfma_f32_16x16x32_bf16 v[114:117], v[162:165], v[222:225], v[114:117]
	v_mfma_f32_16x16x32_bf16 v[82:85], v[170:173], v[222:225], v[82:85]
	s_setprio 0
	s_barrier
	s_add_i32 s30, 0, 0x14000
	s_add_i32 s0, s29, s4
	v_add_u32_e32 v157, s30, v155
	v_lshl_add_u64 v[174:175], s[14:15], 0, v[130:131]
	s_mov_b32 m0, s0
	ds_read_b128 v[226:229], v157
	ds_read_b128 v[230:233], v157 offset:1024
	ds_read_b128 v[234:237], v157 offset:2048
	ds_read_b128 v[238:241], v157 offset:3072
	global_load_lds_dwordx4 v[174:175], off
	s_add_i32 m0, s0, 0x2000
	v_lshl_add_u64 v[192:193], s[14:15], 0, v[132:133]
	global_load_lds_dwordx4 v[192:193], off
	s_barrier
	s_waitcnt lgkmcnt(0)
	s_setprio 1
	v_mfma_f32_16x16x32_bf16 v[78:81], v[226:229], v[194:197], v[78:81]
	v_mfma_f32_16x16x32_bf16 v[54:57], v[234:237], v[194:197], v[54:57]
	v_mfma_f32_16x16x32_bf16 v[74:77], v[226:229], v[202:205], v[74:77]
	v_mfma_f32_16x16x32_bf16 v[46:49], v[234:237], v[202:205], v[46:49]
	v_mfma_f32_16x16x32_bf16 v[66:69], v[226:229], v[210:213], v[66:69]
	v_mfma_f32_16x16x32_bf16 v[38:41], v[234:237], v[210:213], v[38:41]
	v_mfma_f32_16x16x32_bf16 v[58:61], v[226:229], v[218:221], v[58:61]
	v_mfma_f32_16x16x32_bf16 v[34:37], v[234:237], v[218:221], v[34:37]
	v_mfma_f32_16x16x32_bf16 v[78:81], v[230:233], v[198:201], v[78:81]
	v_mfma_f32_16x16x32_bf16 v[54:57], v[238:241], v[198:201], v[54:57]
	v_mfma_f32_16x16x32_bf16 v[74:77], v[230:233], v[206:209], v[74:77]
	v_mfma_f32_16x16x32_bf16 v[46:49], v[238:241], v[206:209], v[46:49]
	v_mfma_f32_16x16x32_bf16 v[66:69], v[230:233], v[214:217], v[66:69]
	v_mfma_f32_16x16x32_bf16 v[38:41], v[238:241], v[214:217], v[38:41]
	v_mfma_f32_16x16x32_bf16 v[58:61], v[230:233], v[222:225], v[58:61]
	v_mfma_f32_16x16x32_bf16 v[34:37], v[238:241], v[222:225], v[34:37]
	s_setprio 0
	s_mov_b32 m0, s7
	v_lshl_add_u64 v[242:243], s[40:41], 0, v[130:131]
	s_barrier
	ds_read_b128 v[194:197], v156 offset:16384
	ds_read_b128 v[198:201], v156 offset:17408
	ds_read_b128 v[202:205], v156 offset:18432
	ds_read_b128 v[206:209], v156 offset:19456
	ds_read_b128 v[210:213], v156 offset:20480
	ds_read_b128 v[214:217], v156 offset:21504
	ds_read_b128 v[218:221], v156 offset:22528
	ds_read_b128 v[222:225], v156 offset:23552
	global_load_lds_dwordx4 v[242:243], off
	s_mov_b32 m0, s17
	v_lshl_add_u64 v[244:245], s[40:41], 0, v[132:133]
	global_load_lds_dwordx4 v[244:245], off
	s_barrier
	s_waitcnt lgkmcnt(0)
	s_setprio 1
	v_mfma_f32_16x16x32_bf16 v[110:113], v[158:161], v[194:197], v[110:113]
	v_mfma_f32_16x16x32_bf16 v[70:73], v[166:169], v[194:197], v[70:73]
	v_mfma_f32_16x16x32_bf16 v[106:109], v[158:161], v[202:205], v[106:109]
	v_mfma_f32_16x16x32_bf16 v[62:65], v[166:169], v[202:205], v[62:65]
	v_mfma_f32_16x16x32_bf16 v[98:101], v[158:161], v[210:213], v[98:101]
	v_mfma_f32_16x16x32_bf16 v[50:53], v[166:169], v[210:213], v[50:53]
	v_mfma_f32_16x16x32_bf16 v[94:97], v[158:161], v[218:221], v[94:97]
	v_mfma_f32_16x16x32_bf16 v[42:45], v[166:169], v[218:221], v[42:45]
	v_mfma_f32_16x16x32_bf16 v[110:113], v[162:165], v[198:201], v[110:113]
	v_mfma_f32_16x16x32_bf16 v[70:73], v[170:173], v[198:201], v[70:73]
	v_mfma_f32_16x16x32_bf16 v[106:109], v[162:165], v[206:209], v[106:109]
	v_mfma_f32_16x16x32_bf16 v[62:65], v[170:173], v[206:209], v[62:65]
	v_mfma_f32_16x16x32_bf16 v[98:101], v[162:165], v[214:217], v[98:101]
	v_mfma_f32_16x16x32_bf16 v[50:53], v[170:173], v[214:217], v[50:53]
	v_mfma_f32_16x16x32_bf16 v[94:97], v[162:165], v[222:225], v[94:97]
	v_mfma_f32_16x16x32_bf16 v[42:45], v[170:173], v[222:225], v[42:45]
	s_setprio 0
	s_barrier
; #define PG8_STAGE(bufoff, gbase) do { _Pragma("unroll") for (int _i = 0; _i < 2; ++_i) \
;         __builtin_amdgcn_global_load_lds((const unsigned*)((const char*)(gbase) + voff[_i]), (LAS unsigned*)(lds + (bufoff) + ldsw + _i * 8192), 16, 0, 0); } while (0)
; #define PG8_LDA(dst, b, h) do { _Pragma("unroll") for (int m = 0; m < 4; ++m) _Pragma("unroll") for (int k = 0; k < 2; ++k) dst[m][k] = *(const LAS bf16x8*)(lds + PG8_SA(b, h) + aoff + m * 2048 + k * 1024); } while (0)
; #define PG8_LDB(dst, b, h) do { _Pragma("unroll") for (int n = 0; n < 2; ++n) _Pragma("unroll") for (int k = 0; k < 2; ++k) dst[n][k] = *(const LAS bf16x8*)(lds + PG8_SB(b, h) + boff + n * 2048 + k * 1024); } while (0)
; #define PG8_WAIT_V(n) asm volatile("s_waitcnt vmcnt(" #n ")" ::: "memory")
; #define PG8_WAIT_L(n) asm volatile("s_waitcnt lgkmcnt(" #n ")" ::: "memory")
; #define PG8_BAR __builtin_amdgcn_s_barrier()
; #define PG8_SCHED __builtin_amdgcn_sched_barrier(0)
;     ...
;             PG8_STAGE(PG8_SB(0, 1), b2 + hstep);
;             PG8_WAIT_V(6); PG8_BAR; PG8_MMA(1, 1, At, B1); PG8_BAR;
;             PG8_LDB(B0, 1, 0); PG8_SCHED; PG8_LDA(At, 1, 0); PG8_STAGE(PG8_SA(0, 1), a2 + hstep);
;             PG8_WAIT_L(8); PG8_BAR; PG8_WAIT_L(0); PG8_MMA(0, 0, At, B0); PG8_BAR; PG8_SCHED;
;             PG8_LDB(B1, 1, 1); PG8_STAGE(PG8_SB(1, 0), b3);
;             PG8_BAR; PG8_WAIT_L(0); PG8_MMA(0, 1, At, B1); PG8_BAR;
;             PG8_LDA(At, 1, 1); PG8_STAGE(PG8_SA(1, 0), a3);
;             PG8_BAR; PG8_WAIT_L(0); PG8_MMA(1, 0, At, B0); PG8_BAR; PG8_SCHED;
	s_add_u32 s0, s14, 0xb0000
	s_addc_u32 s1, s15, 0
	s_add_i32 s29, s30, s4
	s_mov_b32 m0, s29
	v_lshl_add_u64 v[158:159], s[0:1], 0, v[130:131]
	global_load_lds_dwordx4 v[158:159], off
	s_add_i32 m0, s29, 0x2000
	v_lshl_add_u64 v[158:159], s[0:1], 0, v[132:133]
	global_load_lds_dwordx4 v[158:159], off
	s_waitcnt vmcnt(6)
	s_barrier
	s_setprio 1
	v_mfma_f32_16x16x32_bf16 v[30:33], v[226:229], v[194:197], v[30:33]
	v_mfma_f32_16x16x32_bf16 v[14:17], v[234:237], v[194:197], v[14:17]
	v_mfma_f32_16x16x32_bf16 v[26:29], v[226:229], v[202:205], v[26:29]
	v_mfma_f32_16x16x32_bf16 v[10:13], v[234:237], v[202:205], v[10:13]
	v_mfma_f32_16x16x32_bf16 v[22:25], v[226:229], v[210:213], v[22:25]
	v_mfma_f32_16x16x32_bf16 v[6:9], v[234:237], v[210:213], v[6:9]
	v_mfma_f32_16x16x32_bf16 v[18:21], v[226:229], v[218:221], v[18:21]
	v_mfma_f32_16x16x32_bf16 v[2:5], v[234:237], v[218:221], v[2:5]
	v_mfma_f32_16x16x32_bf16 v[30:33], v[230:233], v[198:201], v[30:33]
	v_mfma_f32_16x16x32_bf16 v[14:17], v[238:241], v[198:201], v[14:17]
	v_mfma_f32_16x16x32_bf16 v[26:29], v[230:233], v[206:209], v[26:29]
	v_mfma_f32_16x16x32_bf16 v[10:13], v[238:241], v[206:209], v[10:13]
	v_mfma_f32_16x16x32_bf16 v[22:25], v[230:233], v[214:217], v[22:25]
	v_mfma_f32_16x16x32_bf16 v[6:9], v[238:241], v[214:217], v[6:9]
	v_mfma_f32_16x16x32_bf16 v[18:21], v[230:233], v[222:225], v[18:21]
	v_mfma_f32_16x16x32_bf16 v[2:5], v[238:241], v[222:225], v[2:5]
	s_setprio 0
	s_add_i32 s29, 0, 0x18000
	v_add_u32_e32 v157, s29, v155
	s_barrier
	ds_read_b128 v[158:161], v157
	ds_read_b128 v[162:165], v157 offset:1024
	ds_read_b128 v[166:169], v157 offset:2048
	ds_read_b128 v[170:173], v157 offset:3072
	s_add_u32 s0, s40, 0xb0000
	s_addc_u32 s1, s41, 0
	s_mov_b32 m0, s18
	v_lshl_add_u64 v[226:227], s[0:1], 0, v[130:131]
	ds_read_b128 v[194:197], v156 offset:32768
	ds_read_b128 v[198:201], v156 offset:33792
	ds_read_b128 v[202:205], v156 offset:34816
	ds_read_b128 v[206:209], v156 offset:35840
	ds_read_b128 v[210:213], v156 offset:36864
	ds_read_b128 v[214:217], v156 offset:37888
	ds_read_b128 v[218:221], v156 offset:38912
	ds_read_b128 v[222:225], v156 offset:39936
	global_load_lds_dwordx4 v[226:227], off
	s_mov_b32 m0, s19
	v_lshl_add_u64 v[226:227], s[0:1], 0, v[132:133]
	global_load_lds_dwordx4 v[226:227], off
	s_waitcnt lgkmcnt(8)
	s_barrier
	s_waitcnt lgkmcnt(0)
	s_setprio 1
	v_mfma_f32_16x16x32_bf16 v[126:129], v[158:161], v[194:197], v[126:129]
	v_mfma_f32_16x16x32_bf16 v[102:105], v[166:169], v[194:197], v[102:105]
	v_mfma_f32_16x16x32_bf16 v[122:125], v[158:161], v[202:205], v[122:125]
	v_mfma_f32_16x16x32_bf16 v[90:93], v[166:169], v[202:205], v[90:93]
	v_mfma_f32_16x16x32_bf16 v[118:121], v[158:161], v[210:213], v[118:121]
	v_mfma_f32_16x16x32_bf16 v[86:89], v[166:169], v[210:213], v[86:89]
	v_mfma_f32_16x16x32_bf16 v[114:117], v[158:161], v[218:221], v[114:117]
	v_mfma_f32_16x16x32_bf16 v[82:85], v[166:169], v[218:221], v[82:85]
	v_mfma_f32_16x16x32_bf16 v[126:129], v[162:165], v[198:201], v[126:129]
	v_mfma_f32_16x16x32_bf16 v[102:105], v[170:173], v[198:201], v[102:105]
	v_mfma_f32_16x16x32_bf16 v[122:125], v[162:165], v[206:209], v[122:125]
	v_mfma_f32_16x16x32_bf16 v[90:93], v[170:173], v[206:209], v[90:93]
	v_mfma_f32_16x16x32_bf16 v[118:121], v[162:165], v[214:217], v[118:121]
	v_mfma_f32_16x16x32_bf16 v[86:89], v[170:173], v[214:217], v[86:89]
	v_mfma_f32_16x16x32_bf16 v[114:117], v[162:165], v[222:225], v[114:117]
	v_mfma_f32_16x16x32_bf16 v[82:85], v[170:173], v[222:225], v[82:85]
	s_setprio 0
	s_barrier
	s_add_i32 s30, 0, 0x1c000
	s_add_i32 s0, s29, s4
	v_add_u32_e32 v157, s30, v155
	v_lshl_add_u64 v[174:175], v[174:175], 0, s[88:89]
	s_mov_b32 m0, s0
	ds_read_b128 v[226:229], v157
	ds_read_b128 v[230:233], v157 offset:1024
	ds_read_b128 v[234:237], v157 offset:2048
	ds_read_b128 v[238:241], v157 offset:3072
	global_load_lds_dwordx4 v[174:175], off
	s_add_i32 m0, s0, 0x2000
	v_lshl_add_u64 v[174:175], v[192:193], 0, s[88:89]
	global_load_lds_dwordx4 v[174:175], off
	s_barrier
	s_waitcnt lgkmcnt(0)
	s_setprio 1
	v_mfma_f32_16x16x32_bf16 v[78:81], v[226:229], v[194:197], v[78:81]
	v_mfma_f32_16x16x32_bf16 v[54:57], v[234:237], v[194:197], v[54:57]
	v_mfma_f32_16x16x32_bf16 v[74:77], v[226:229], v[202:205], v[74:77]
	v_mfma_f32_16x16x32_bf16 v[46:49], v[234:237], v[202:205], v[46:49]
	v_mfma_f32_16x16x32_bf16 v[66:69], v[226:229], v[210:213], v[66:69]
	v_mfma_f32_16x16x32_bf16 v[38:41], v[234:237], v[210:213], v[38:41]
	v_mfma_f32_16x16x32_bf16 v[58:61], v[226:229], v[218:221], v[58:61]
	v_mfma_f32_16x16x32_bf16 v[34:37], v[234:237], v[218:221], v[34:37]
	v_mfma_f32_16x16x32_bf16 v[78:81], v[230:233], v[198:201], v[78:81]
	v_mfma_f32_16x16x32_bf16 v[54:57], v[238:241], v[198:201], v[54:57]
	v_mfma_f32_16x16x32_bf16 v[74:77], v[230:233], v[206:209], v[74:77]
	v_mfma_f32_16x16x32_bf16 v[46:49], v[238:241], v[206:209], v[46:49]
	v_mfma_f32_16x16x32_bf16 v[66:69], v[230:233], v[214:217], v[66:69]
	v_mfma_f32_16x16x32_bf16 v[38:41], v[238:241], v[214:217], v[38:41]
	v_mfma_f32_16x16x32_bf16 v[58:61], v[230:233], v[222:225], v[58:61]
	v_mfma_f32_16x16x32_bf16 v[34:37], v[238:241], v[222:225], v[34:37]
	s_setprio 0
	s_mov_b32 m0, s22
	v_lshl_add_u64 v[174:175], v[242:243], 0, s[88:89]
	s_barrier
	ds_read_b128 v[194:197], v156 offset:49152
	ds_read_b128 v[198:201], v156 offset:50176
	ds_read_b128 v[202:205], v156 offset:51200
	ds_read_b128 v[206:209], v156 offset:52224
	ds_read_b128 v[210:213], v156 offset:53248
	ds_read_b128 v[214:217], v156 offset:54272
	ds_read_b128 v[218:221], v156 offset:55296
	ds_read_b128 v[222:225], v156 offset:56320
	global_load_lds_dwordx4 v[174:175], off
	s_mov_b32 m0, s23
	v_lshl_add_u64 v[174:175], v[244:245], 0, s[88:89]
	global_load_lds_dwordx4 v[174:175], off
	s_barrier
; #define PG8_STAGE(bufoff, gbase) do { _Pragma("unroll") for (int _i = 0; _i < 2; ++_i) \
;         __builtin_amdgcn_global_load_lds((const unsigned*)((const char*)(gbase) + voff[_i]), (LAS unsigned*)(lds + (bufoff) + ldsw + _i * 8192), 16, 0, 0); } while (0)
; #define PG8_WAIT_V(n) asm volatile("s_waitcnt vmcnt(" #n ")" ::: "memory")
; #define PG8_WAIT_L(n) asm volatile("s_waitcnt lgkmcnt(" #n ")" ::: "memory")
; #define PG8_BAR __builtin_amdgcn_s_barrier()
; #define PG8_SCHED __builtin_amdgcn_sched_barrier(0)
;     ...
;             PG8_BAR; PG8_WAIT_L(0); PG8_MMA(1, 0, At, B0); PG8_BAR; PG8_SCHED;
;             PG8_STAGE(PG8_SB(1, 1), b3 + hstep);
;             PG8_WAIT_V(6); PG8_BAR; PG8_MMA(1, 1, At, B1); PG8_BAR;
;         }
;         E(acc, cur.pm + pm0, cur.pn, wr, wc, fr, fq);
;     __device__ __forceinline__ void operator()(Acc& acc, int pm, int pn, int wr, int wc, int fr, int fq) const {
;         const int brow = pm * 256;
;         const bool lat = brow < T_LAT;
;         const float* xin = lat ? xin_lat : xin_ctx;
;         float* xout = lat ? xout_lat : xout_ctx;
;         const int rsub = lat ? 0 : T_LAT;
;         const int mi = lat ? (brow >> 12) : 8;
;         const int c0 = pn * 256 + wc * 32 + fq * 4;
;         const float* gp = modv_l + (size_t)mi * 6144 + gate_i * 1024 + c0;
; #pragma unroll
;         for (int bj = 0; bj < 2; ++bj)
; #pragma unroll
;             for (int n = 0; n < 2; ++n) {
;                 const f32x4 gv = *reinterpret_cast<const f32x4*>(gp + bj * 128 + n * 16);
; #pragma unroll
;                 for (int ai = 0; ai < 2; ++ai)
; #pragma unroll
;                     for (int m = 0; m < 4; ++m) {
;                         const size_t o = (size_t)(brow + ai * 128 + wr * 64 + m * 16 + fr - rsub) * DM + c0 + bj * 128 + n * 16;
;                         const f32x4 xi = *reinterpret_cast<const f32x4*>(xin + o);
;                         const f32x4 a = acc[ai][bj][m][n];
;                         f32x4 r = {xi[0] + gv[0] * a[0], xi[1] + gv[1] * a[1], xi[2] + gv[2] * a[2], xi[3] + gv[3] * a[3]};
;                         *reinterpret_cast<f32x4*>(xout + o) = r;
	s_waitcnt lgkmcnt(0)
	s_setprio 1
	v_mfma_f32_16x16x32_bf16 v[110:113], v[158:161], v[194:197], v[110:113]
	v_mfma_f32_16x16x32_bf16 v[70:73], v[166:169], v[194:197], v[70:73]
	v_mfma_f32_16x16x32_bf16 v[106:109], v[158:161], v[202:205], v[106:109]
	v_mfma_f32_16x16x32_bf16 v[62:65], v[166:169], v[202:205], v[62:65]
	v_mfma_f32_16x16x32_bf16 v[98:101], v[158:161], v[210:213], v[98:101]
	v_mfma_f32_16x16x32_bf16 v[50:53], v[166:169], v[210:213], v[50:53]
	v_mfma_f32_16x16x32_bf16 v[94:97], v[158:161], v[218:221], v[94:97]
	v_mfma_f32_16x16x32_bf16 v[42:45], v[166:169], v[218:221], v[42:45]
	v_mfma_f32_16x16x32_bf16 v[110:113], v[162:165], v[198:201], v[110:113]
	v_mfma_f32_16x16x32_bf16 v[70:73], v[170:173], v[198:201], v[70:73]
	v_mfma_f32_16x16x32_bf16 v[106:109], v[162:165], v[206:209], v[106:109]
	v_mfma_f32_16x16x32_bf16 v[62:65], v[170:173], v[206:209], v[62:65]
	v_mfma_f32_16x16x32_bf16 v[98:101], v[162:165], v[214:217], v[98:101]
	v_mfma_f32_16x16x32_bf16 v[50:53], v[170:173], v[214:217], v[50:53]
	v_mfma_f32_16x16x32_bf16 v[94:97], v[162:165], v[222:225], v[94:97]
	v_mfma_f32_16x16x32_bf16 v[42:45], v[170:173], v[222:225], v[42:45]
	s_setprio 0
	s_barrier
	s_add_u32 s0, s14, 0xb0080
	s_addc_u32 s1, s15, 0
	s_add_i32 s14, s30, s4
	s_mov_b32 m0, s14
	v_lshl_add_u64 v[158:159], s[0:1], 0, v[130:131]
	global_load_lds_dwordx4 v[158:159], off
	s_add_i32 m0, s14, 0x2000
	v_lshl_add_u64 v[158:159], s[0:1], 0, v[132:133]
	global_load_lds_dwordx4 v[158:159], off
	s_waitcnt vmcnt(6)
	s_barrier
	s_setprio 1
	v_mfma_f32_16x16x32_bf16 v[30:33], v[226:229], v[194:197], v[30:33]
	v_mfma_f32_16x16x32_bf16 v[14:17], v[234:237], v[194:197], v[14:17]
	v_mfma_f32_16x16x32_bf16 v[26:29], v[226:229], v[202:205], v[26:29]
	v_mfma_f32_16x16x32_bf16 v[10:13], v[234:237], v[202:205], v[10:13]
	v_mfma_f32_16x16x32_bf16 v[22:25], v[226:229], v[210:213], v[22:25]
	v_mfma_f32_16x16x32_bf16 v[6:9], v[234:237], v[210:213], v[6:9]
	v_mfma_f32_16x16x32_bf16 v[18:21], v[226:229], v[218:221], v[18:21]
	v_mfma_f32_16x16x32_bf16 v[2:5], v[234:237], v[218:221], v[2:5]
	v_mfma_f32_16x16x32_bf16 v[30:33], v[230:233], v[198:201], v[30:33]
	v_mfma_f32_16x16x32_bf16 v[14:17], v[238:241], v[198:201], v[14:17]
	v_mfma_f32_16x16x32_bf16 v[26:29], v[230:233], v[206:209], v[26:29]
	v_mfma_f32_16x16x32_bf16 v[10:13], v[238:241], v[206:209], v[10:13]
	v_mfma_f32_16x16x32_bf16 v[22:25], v[230:233], v[214:217], v[22:25]
	v_mfma_f32_16x16x32_bf16 v[6:9], v[238:241], v[214:217], v[6:9]
	v_mfma_f32_16x16x32_bf16 v[18:21], v[230:233], v[222:225], v[18:21]
	v_mfma_f32_16x16x32_bf16 v[2:5], v[238:241], v[222:225], v[2:5]
	s_setprio 0
	s_add_i32 s28, s28, 2
	s_add_u32 s12, s12, 0x100
	s_addc_u32 s13, s13, 0
	s_cmp_gt_u32 s28, 41
	s_barrier
	s_cbranch_scc0 .LBB0_1832
	v_readlane_b32 s0, v253, 63
	v_readlane_b32 s64, v254, 6
	v_readlane_b32 s68, v254, 10
	v_readlane_b32 s69, v254, 11
	v_readlane_b32 s65, v254, 7
	v_readlane_b32 s66, v254, 8
	v_readlane_b32 s67, v254, 9
	v_readlane_b32 s70, v254, 12
	v_readlane_b32 s71, v254, 13
	v_mov_b32_e32 v161, v0
	v_lshl_or_b32 v157, v154, 2, s0
	v_or_b32_e32 v157, s20, v157
	v_lshlrev_b32_e32 v160, 2, v157
	v_readlane_b32 s0, v253, 61
	s_nop 1
	v_lshl_add_u64 v[158:159], s[50:51], 0, v[160:161]
	v_add_u32_e32 v162, s0, v1
	s_mov_b64 s[0:1], 0x35000
	v_lshl_add_u64 v[158:159], v[158:159], 0, s[0:1]
	global_load_dwordx4 v[192:195], v[158:159], off
	global_load_dwordx4 v[196:199], v[158:159], off offset:64
	global_load_dwordx4 v[200:203], v[158:159], off offset:512
	global_load_dwordx4 v[204:207], v[158:159], off offset:576
	v_add_u32_e32 v163, 0xffff8000, v162
	v_lshl_or_b32 v164, v163, 12, v160
	v_add_u32_e32 v165, 0x10000, v164
	v_add_u32_e32 v166, 0x20000, v164
	v_add_u32_e32 v167, 0x30000, v164
	v_add_u32_e32 v168, 0x80000, v164
	v_add_u32_e32 v169, 0x90000, v164
	v_add_u32_e32 v170, 0xa0000, v164
	v_add_u32_e32 v171, 0xb0000, v164
	global_load_dwordx4 v[208:211], v164, s[68:69]
	global_load_dwordx4 v[212:215], v164, s[68:69] offset:64
	global_load_dwordx4 v[216:219], v165, s[68:69]
	global_load_dwordx4 v[220:223], v165, s[68:69] offset:64
	global_load_dwordx4 v[224:227], v166, s[68:69]
	global_load_dwordx4 v[228:231], v166, s[68:69] offset:64
	global_load_dwordx4 v[232:235], v167, s[68:69]
	global_load_dwordx4 v[236:239], v167, s[68:69] offset:64
	global_load_dwordx4 v[240:243], v168, s[68:69]
	s_cmpk_lt_u32 s16, 0x100
	s_waitcnt vmcnt(8)
	v_pk_fma_f32 v[126:127], v[126:127], v[192:193], v[208:209]
	v_pk_fma_f32 v[128:129], v[128:129], v[194:195], v[210:211]
	global_store_dwordx4 v164, v[126:129], s[68:69]
	global_load_dwordx4 v[208:211], v168, s[68:69] offset:64
	s_waitcnt vmcnt(9)
	v_pk_fma_f32 v[102:103], v[102:103], v[196:197], v[212:213]
	v_pk_fma_f32 v[104:105], v[104:105], v[198:199], v[214:215]
	global_store_dwordx4 v164, v[102:105], s[68:69] offset:64
	global_load_dwordx4 v[212:215], v169, s[68:69]
	s_waitcnt vmcnt(10)
	v_pk_fma_f32 v[122:123], v[122:123], v[192:193], v[216:217]
	v_pk_fma_f32 v[124:125], v[124:125], v[194:195], v[218:219]
	global_store_dwordx4 v165, v[122:125], s[68:69]
	global_load_dwordx4 v[216:219], v169, s[68:69] offset:64
	s_waitcnt vmcnt(11)
	v_pk_fma_f32 v[90:91], v[90:91], v[196:197], v[220:221]
	v_pk_fma_f32 v[92:93], v[92:93], v[198:199], v[222:223]
	global_store_dwordx4 v165, v[90:93], s[68:69] offset:64
	global_load_dwordx4 v[220:223], v170, s[68:69]
	s_waitcnt vmcnt(12)
	v_pk_fma_f32 v[118:119], v[118:119], v[192:193], v[224:225]
	v_pk_fma_f32 v[120:121], v[120:121], v[194:195], v[226:227]
	global_store_dwordx4 v166, v[118:121], s[68:69]
	global_load_dwordx4 v[224:227], v170, s[68:69] offset:64
	s_waitcnt vmcnt(13)
;     __device__ __forceinline__ void operator()(Acc& acc, int pm, int pn, int wr, int wc, int fr, int fq) const {
;     ...
; #pragma unroll
;         for (int bj = 0; bj < 2; ++bj)
; #pragma unroll
;             for (int n = 0; n < 2; ++n) {
;                 const f32x4 gv = *reinterpret_cast<const f32x4*>(gp + bj * 128 + n * 16);
; #pragma unroll
;                 for (int ai = 0; ai < 2; ++ai)
; #pragma unroll
;                     for (int m = 0; m < 4; ++m) {
;                         const size_t o = (size_t)(brow + ai * 128 + wr * 64 + m * 16 + fr - rsub) * DM + c0 + bj * 128 + n * 16;
;                         const f32x4 xi = *reinterpret_cast<const f32x4*>(xin + o);
;                         const f32x4 a = acc[ai][bj][m][n];
;                         f32x4 r = {xi[0] + gv[0] * a[0], xi[1] + gv[1] * a[1], xi[2] + gv[2] * a[2], xi[3] + gv[3] * a[3]};
;                         *reinterpret_cast<f32x4*>(xout + o) = r;
;                     }
	v_pk_fma_f32 v[86:87], v[86:87], v[196:197], v[228:229]
	v_pk_fma_f32 v[88:89], v[88:89], v[198:199], v[230:231]
	global_store_dwordx4 v166, v[86:89], s[68:69] offset:64
	global_load_dwordx4 v[228:231], v171, s[68:69]
	s_waitcnt vmcnt(14)
	v_pk_fma_f32 v[114:115], v[114:115], v[192:193], v[232:233]
	v_pk_fma_f32 v[116:117], v[116:117], v[194:195], v[234:235]
	global_store_dwordx4 v167, v[114:117], s[68:69]
	global_load_dwordx4 v[232:235], v171, s[68:69] offset:64
	s_waitcnt vmcnt(15)
	v_pk_fma_f32 v[82:83], v[82:83], v[196:197], v[236:237]
	v_pk_fma_f32 v[84:85], v[84:85], v[198:199], v[238:239]
	global_store_dwordx4 v167, v[82:85], s[68:69] offset:64
	global_load_dwordx4 v[236:239], v164, s[68:69] offset:512
	s_waitcnt vmcnt(16)
	v_pk_fma_f32 v[110:111], v[110:111], v[192:193], v[240:241]
	v_pk_fma_f32 v[112:113], v[112:113], v[194:195], v[242:243]
	global_store_dwordx4 v168, v[110:113], s[68:69]
	global_load_dwordx4 v[240:243], v164, s[68:69] offset:576
	s_waitcnt vmcnt(16)
	v_pk_fma_f32 v[70:71], v[70:71], v[196:197], v[208:209]
	v_pk_fma_f32 v[72:73], v[72:73], v[198:199], v[210:211]
	global_store_dwordx4 v168, v[70:73], s[68:69] offset:64
	global_load_dwordx4 v[208:211], v165, s[68:69] offset:512
	s_waitcnt vmcnt(16)
	v_pk_fma_f32 v[106:107], v[106:107], v[192:193], v[212:213]
	v_pk_fma_f32 v[108:109], v[108:109], v[194:195], v[214:215]
	global_store_dwordx4 v169, v[106:109], s[68:69]
	global_load_dwordx4 v[212:215], v165, s[68:69] offset:576
	s_waitcnt vmcnt(16)
	v_pk_fma_f32 v[62:63], v[62:63], v[196:197], v[216:217]
	v_pk_fma_f32 v[64:65], v[64:65], v[198:199], v[218:219]
	global_store_dwordx4 v169, v[62:65], s[68:69] offset:64
	global_load_dwordx4 v[216:219], v166, s[68:69] offset:512
	s_waitcnt vmcnt(16)
	v_pk_fma_f32 v[98:99], v[98:99], v[192:193], v[220:221]
	v_pk_fma_f32 v[100:101], v[100:101], v[194:195], v[222:223]
	global_store_dwordx4 v170, v[98:101], s[68:69]
	global_load_dwordx4 v[220:223], v166, s[68:69] offset:576
	s_waitcnt vmcnt(16)
	v_pk_fma_f32 v[50:51], v[50:51], v[196:197], v[224:225]
	v_pk_fma_f32 v[52:53], v[52:53], v[198:199], v[226:227]
	global_store_dwordx4 v170, v[50:53], s[68:69] offset:64
	global_load_dwordx4 v[224:227], v167, s[68:69] offset:512
	s_waitcnt vmcnt(16)
	v_pk_fma_f32 v[94:95], v[94:95], v[192:193], v[228:229]
	v_pk_fma_f32 v[96:97], v[96:97], v[194:195], v[230:231]
	global_store_dwordx4 v171, v[94:97], s[68:69]
	global_load_dwordx4 v[228:231], v167, s[68:69] offset:576
	s_waitcnt vmcnt(16)
	v_pk_fma_f32 v[42:43], v[42:43], v[196:197], v[232:233]
	v_pk_fma_f32 v[44:45], v[44:45], v[198:199], v[234:235]
	global_store_dwordx4 v171, v[42:45], s[68:69] offset:64
	global_load_dwordx4 v[232:235], v168, s[68:69] offset:512
	s_waitcnt vmcnt(16)
	v_pk_fma_f32 v[78:79], v[78:79], v[200:201], v[236:237]
	v_pk_fma_f32 v[80:81], v[80:81], v[202:203], v[238:239]
	global_store_dwordx4 v164, v[78:81], s[68:69] offset:512
	global_load_dwordx4 v[236:239], v168, s[68:69] offset:576
	s_waitcnt vmcnt(16)
	v_pk_fma_f32 v[54:55], v[54:55], v[204:205], v[240:241]
	v_pk_fma_f32 v[56:57], v[56:57], v[206:207], v[242:243]
	global_store_dwordx4 v164, v[54:57], s[68:69] offset:576
	global_load_dwordx4 v[240:243], v169, s[68:69] offset:512
	s_waitcnt vmcnt(16)
	v_pk_fma_f32 v[74:75], v[74:75], v[200:201], v[208:209]
	v_pk_fma_f32 v[76:77], v[76:77], v[202:203], v[210:211]
	global_store_dwordx4 v165, v[74:77], s[68:69] offset:512
	global_load_dwordx4 v[208:211], v169, s[68:69] offset:576
	s_waitcnt vmcnt(16)
	v_pk_fma_f32 v[46:47], v[46:47], v[204:205], v[212:213]
	v_pk_fma_f32 v[48:49], v[48:49], v[206:207], v[214:215]
	global_store_dwordx4 v165, v[46:49], s[68:69] offset:576
	global_load_dwordx4 v[212:215], v170, s[68:69] offset:512
	s_waitcnt vmcnt(16)
	v_pk_fma_f32 v[66:67], v[66:67], v[200:201], v[216:217]
	v_pk_fma_f32 v[68:69], v[68:69], v[202:203], v[218:219]
	global_store_dwordx4 v166, v[66:69], s[68:69] offset:512
	global_load_dwordx4 v[216:219], v170, s[68:69] offset:576
	s_waitcnt vmcnt(16)
	v_pk_fma_f32 v[38:39], v[38:39], v[204:205], v[220:221]
	v_pk_fma_f32 v[40:41], v[40:41], v[206:207], v[222:223]
	global_store_dwordx4 v166, v[38:41], s[68:69] offset:576
	global_load_dwordx4 v[220:223], v171, s[68:69] offset:512
	s_waitcnt vmcnt(16)
	v_pk_fma_f32 v[58:59], v[58:59], v[200:201], v[224:225]
	v_pk_fma_f32 v[60:61], v[60:61], v[202:203], v[226:227]
	global_store_dwordx4 v167, v[58:61], s[68:69] offset:512
	global_load_dwordx4 v[224:227], v171, s[68:69] offset:576
	s_waitcnt vmcnt(16)
	v_pk_fma_f32 v[34:35], v[34:35], v[204:205], v[228:229]
	v_pk_fma_f32 v[36:37], v[36:37], v[206:207], v[230:231]
	global_store_dwordx4 v167, v[34:37], s[68:69] offset:576
	s_waitcnt vmcnt(15)
	v_pk_fma_f32 v[30:31], v[30:31], v[200:201], v[232:233]
	v_pk_fma_f32 v[32:33], v[32:33], v[202:203], v[234:235]
	global_store_dwordx4 v168, v[30:33], s[68:69] offset:512
	s_waitcnt vmcnt(14)
	v_pk_fma_f32 v[14:15], v[14:15], v[204:205], v[236:237]
	v_pk_fma_f32 v[16:17], v[16:17], v[206:207], v[238:239]
	global_store_dwordx4 v168, v[14:17], s[68:69] offset:576
	s_waitcnt vmcnt(13)
	v_pk_fma_f32 v[26:27], v[26:27], v[200:201], v[240:241]
	v_pk_fma_f32 v[28:29], v[28:29], v[202:203], v[242:243]
	global_store_dwordx4 v169, v[26:29], s[68:69] offset:512
	s_waitcnt vmcnt(12)
	v_pk_fma_f32 v[10:11], v[10:11], v[204:205], v[208:209]
	v_pk_fma_f32 v[12:13], v[12:13], v[206:207], v[210:211]
	global_store_dwordx4 v169, v[10:13], s[68:69] offset:576
	s_waitcnt vmcnt(11)
	v_pk_fma_f32 v[22:23], v[22:23], v[200:201], v[212:213]
	v_pk_fma_f32 v[24:25], v[24:25], v[202:203], v[214:215]
	global_store_dwordx4 v170, v[22:25], s[68:69] offset:512
	s_waitcnt vmcnt(10)
	v_pk_fma_f32 v[6:7], v[6:7], v[204:205], v[216:217]
	v_pk_fma_f32 v[8:9], v[8:9], v[206:207], v[218:219]
	global_store_dwordx4 v170, v[6:9], s[68:69] offset:576
	s_waitcnt vmcnt(9)
	v_pk_fma_f32 v[18:19], v[18:19], v[200:201], v[220:221]
	v_pk_fma_f32 v[20:21], v[20:21], v[202:203], v[222:223]
	global_store_dwordx4 v171, v[18:21], s[68:69] offset:512
	s_waitcnt vmcnt(8)
	v_pk_fma_f32 v[2:3], v[2:3], v[204:205], v[224:225]
	v_pk_fma_f32 v[4:5], v[4:5], v[206:207], v[226:227]
	global_store_dwordx4 v171, v[2:5], s[68:69] offset:576
	s_mov_b32 s0, 0xf80b0000
	s_mov_b32 s1, -1
	s_waitcnt vmcnt(0)
	s_cbranch_scc0 .LBB0_1835
	s_barrier
